# GEMM K-loop: closing barrier of each 32-MFMA block moved up 4 MFMAs (prio 2) so the partner half is released early
# baseline (speedup 1.0000x reference)
;     __host__ __device__ __forceinline__ bool next(int i, Unit& u) const { const int vv = vid + (i / 5) * G; if (vv >= 256) return false; u.pm = vv >> 2; u.pn = (vv & 3) + 4 * (i % 5); return true; }
; #define PG8_STAGE(bufoff, gbase, voff) do { _Pragma("unroll") for (int _i = 0; _i < 2; ++_i) \
;         __builtin_amdgcn_global_load_lds((const unsigned*)((const char*)(gbase) + (voff)[_i]), (PG8_LAS unsigned*)(lds + (bufoff) + ldsw + _i * 8192), 16, 0, 0); } while (0)
; #define PG8_BAR __builtin_amdgcn_s_barrier()
;     ...
;         const bool has_next = S.next(ui + 1, nxt);
;         const char* nA = has_next ? (const char*)g.A + (size_t)nxt.pm * tstepA + (size_t)nxt.pn * APN + kofA : cA; const char* nB = has_next ? (const char*)g.Bt + (size_t)nxt.pn * tstepB + S.b_off(nxt) + kofB : cB;
;         for (int t = 0; t < nt; t += 2) {
;             const bool last = (t == nt - 2);
;             const char* a1 = cA + (ptrdiff_t)(t + 1) * kstepA;
;             const char* a2 = last ? nA : cA + (ptrdiff_t)(t + 2) * kstepA; const char* b2 = last ? nB : cB + (ptrdiff_t)(t + 2) * kstep;
;             const char* a3 = a2 + kstepA; const char* b3 = b2 + kstep;
;             if (last && has_next) S.a_ready(nxt);
;             if constexpr (SP2) {
;             PG8_LDB(B0, 0, 0); PG8_LDB(B1, 0, 1); PG8_SCHED; PG8_LDA(At, 0, 0); PG8_STAGE(PG8_SA(1, 1), a1 + hstepA, voffA);
;             PG8_WAIT_V(8); PG8_WAIT_L(0); PG8_BAR; PG8_MMA(0, 0, At, B0); PG8_MMA(0, 1, At, B1); PG8_BAR; PG8_SCHED;
;             PG8_LDA(At, 0, 1); PG8_STAGE(PG8_SB(0, 0), b2, voffB); PG8_STAGE(PG8_SB(0, 1), b2 + hstepB, voffB); PG8_STAGE(PG8_SA(0, 0), a2, voffA);
;             PG8_WAIT_V(8); PG8_WAIT_L(0); PG8_BAR; PG8_MMA(1, 0, At, B0); PG8_MMA(1, 1, At, B1); PG8_BAR; PG8_SCHED;
;             PG8_LDB(B0, 1, 0); PG8_LDB(B1, 1, 1); PG8_SCHED; PG8_LDA(At, 1, 0); PG8_STAGE(PG8_SA(0, 1), a2 + hstepA, voffA);
;             PG8_WAIT_V(8); PG8_WAIT_L(0); PG8_BAR; PG8_MMA(0, 0, At, B0); PG8_MMA(0, 1, At, B1); PG8_BAR; PG8_SCHED;
;             PG8_LDA(At, 1, 1); PG8_STAGE(PG8_SB(1, 0), b3, voffB); PG8_STAGE(PG8_SB(1, 1), b3 + hstepB, voffB); PG8_STAGE(PG8_SA(1, 0), a3, voffA);
;             PG8_WAIT_V(8); PG8_WAIT_L(0); PG8_BAR; PG8_MMA(1, 0, At, B0); PG8_MMA(1, 1, At, B1); PG8_BAR; PG8_SCHED;
;     __device__ __forceinline__ size_t b_off(const pg8::Unit& u) const { return (size_t)(u.pm >> 3) * 4 * 131072; }
.LBB0_97:
	s_mov_b64 s[30:31], s[6:7]
	s_ashr_i32 s6, s14, 2
	s_and_b32 s6, s6, -8
	s_and_b32 s7, s14, 7
	s_mov_b32 s20, s58
	s_mov_b32 s21, s57
	v_cmp_lt_i64_e64 s[4:5], s[14:15], v[138:139]
	s_bfe_u32 s57, s14, 0x20003
	s_or_b32 s58, s6, s7
	s_and_b64 s[6:7], s[4:5], exec
	s_cselect_b32 s24, s58, s20
	s_cselect_b32 s6, s57, s21
	s_ashr_i32 s25, s24, 31
	s_lshl_b64 s[20:21], s[24:25], 20
	s_add_u32 s20, s2, s20
	s_addc_u32 s21, s3, s21
	s_ashr_i32 s7, s6, 31
	s_lshl_b64 s[6:7], s[6:7], 17
	s_add_u32 s20, s20, s6
	s_addc_u32 s21, s21, s7
	s_and_b64 s[28:29], s[4:5], exec
	ds_read_b128 v[0:3], v141
	ds_read_b128 v[4:7], v141 offset:1024
	ds_read_b128 v[8:11], v141 offset:2048
	ds_read_b128 v[12:15], v141 offset:3072
	ds_read_b128 v[16:19], v142
	ds_read_b128 v[20:23], v142 offset:1024
	ds_read_b128 v[24:27], v142 offset:2048
	ds_read_b128 v[28:31], v142 offset:3072
	s_cselect_b32 s29, s21, s27
	s_cselect_b32 s28, s20, s26
	s_add_u32 s25, s33, s6
	s_addc_u32 s34, s36, s7
	s_ashr_i32 s6, s24, 3
	s_ashr_i32 s7, s6, 31
	s_lshl_b64 s[6:7], s[6:7], 19
	s_add_u32 s6, s25, s6
	s_addc_u32 s7, s34, s7
	s_and_b64 s[24:25], s[4:5], exec
	s_cselect_b32 s25, s7, s31
	s_cselect_b32 s24, s6, s30
	s_add_u32 s60, s26, 0x10000
	s_addc_u32 s61, s27, 0
	s_add_u32 s34, s26, 0x18000
	s_addc_u32 s35, s27, 0
	s_add_u32 s62, s26, 0xc000
	s_addc_u32 s63, s27, 0
	s_mov_b32 m0, s46
	v_lshl_add_u64 v[64:65], s[62:63], 0, v[134:135]
	ds_read_b128 v[32:35], v143
	ds_read_b128 v[36:39], v143 offset:1024
	ds_read_b128 v[40:43], v143 offset:2048
	ds_read_b128 v[44:47], v143 offset:3072
	ds_read_b128 v[48:51], v143 offset:4096
	ds_read_b128 v[52:55], v143 offset:5120
	ds_read_b128 v[56:59], v143 offset:6144
	ds_read_b128 v[60:63], v143 offset:7168
	global_load_lds_dwordx4 v[64:65], off
	v_lshl_add_u64 v[64:65], s[62:63], 0, v[130:131]
	s_mov_b32 m0, s47
	s_nop 0
	global_load_lds_dwordx4 v[64:65], off
	s_waitcnt vmcnt(8)
	s_waitcnt lgkmcnt(0)
	s_barrier
	s_setprio 1
	s_waitcnt lgkmcnt(0)
	v_mfma_f32_16x16x32_bf16 v[64:67], v[0:3], v[32:35], 0
	v_mfma_f32_16x16x32_bf16 v[68:71], v[8:11], v[32:35], 0
	v_mfma_f32_16x16x32_bf16 v[72:75], v[0:3], v[40:43], 0
	v_mfma_f32_16x16x32_bf16 v[76:79], v[8:11], v[40:43], 0
	v_mfma_f32_16x16x32_bf16 v[80:83], v[0:3], v[48:51], 0
	v_mfma_f32_16x16x32_bf16 v[84:87], v[8:11], v[48:51], 0
	v_mfma_f32_16x16x32_bf16 v[88:91], v[0:3], v[56:59], 0
	v_mfma_f32_16x16x32_bf16 v[92:95], v[8:11], v[56:59], 0
	v_mfma_f32_16x16x32_bf16 v[64:67], v[4:7], v[36:39], v[64:67]
	v_mfma_f32_16x16x32_bf16 v[68:71], v[12:15], v[36:39], v[68:71]
	v_mfma_f32_16x16x32_bf16 v[72:75], v[4:7], v[44:47], v[72:75]
	v_mfma_f32_16x16x32_bf16 v[76:79], v[12:15], v[44:47], v[76:79]
	v_mfma_f32_16x16x32_bf16 v[80:83], v[4:7], v[52:55], v[80:83]
	v_mfma_f32_16x16x32_bf16 v[84:87], v[12:15], v[52:55], v[84:87]
	v_mfma_f32_16x16x32_bf16 v[88:91], v[4:7], v[60:63], v[88:91]
	v_mfma_f32_16x16x32_bf16 v[92:95], v[12:15], v[60:63], v[92:95]
	s_setprio 0
	s_setprio 1
	v_mfma_f32_16x16x32_bf16 v[96:99], v[16:19], v[32:35], 0
	v_mfma_f32_16x16x32_bf16 v[32:35], v[24:27], v[32:35], 0
	v_mfma_f32_16x16x32_bf16 v[96:99], v[20:23], v[36:39], v[96:99]
	v_mfma_f32_16x16x32_bf16 v[32:35], v[28:31], v[36:39], v[32:35]
	v_mfma_f32_16x16x32_bf16 v[36:39], v[16:19], v[40:43], 0
	v_mfma_f32_16x16x32_bf16 v[40:43], v[24:27], v[40:43], 0
	v_mfma_f32_16x16x32_bf16 v[36:39], v[20:23], v[44:47], v[36:39]
	v_mfma_f32_16x16x32_bf16 v[40:43], v[28:31], v[44:47], v[40:43]
	v_mfma_f32_16x16x32_bf16 v[44:47], v[16:19], v[48:51], 0
	v_mfma_f32_16x16x32_bf16 v[48:51], v[24:27], v[48:51], 0
	v_mfma_f32_16x16x32_bf16 v[44:47], v[20:23], v[52:55], v[44:47]
	v_mfma_f32_16x16x32_bf16 v[48:51], v[28:31], v[52:55], v[48:51]
	s_setprio 2
	s_barrier
	v_mfma_f32_16x16x32_bf16 v[52:55], v[16:19], v[56:59], 0
	v_mfma_f32_16x16x32_bf16 v[56:59], v[24:27], v[56:59], 0
	v_mfma_f32_16x16x32_bf16 v[52:55], v[20:23], v[60:63], v[52:55]
	v_mfma_f32_16x16x32_bf16 v[56:59], v[28:31], v[60:63], v[56:59]
	s_setprio 0
	s_nop 0
	v_lshl_add_u64 v[210:211], s[30:31], 0, v[132:133]
	s_mov_b32 m0, s48
	v_lshl_add_u64 v[146:147], v[210:211], 0, s[16:17]
	v_lshl_add_u64 v[212:213], s[30:31], 0, v[128:129]
	s_add_u32 s62, s30, 0x10100
	ds_read_b128 v[60:63], v143 offset:16384
	ds_read_b128 v[100:103], v143 offset:17408
	ds_read_b128 v[104:107], v143 offset:18432
	ds_read_b128 v[108:111], v143 offset:19456
	ds_read_b128 v[112:115], v143 offset:20480
	ds_read_b128 v[116:119], v143 offset:21504
	ds_read_b128 v[120:123], v143 offset:22528
	ds_read_b128 v[124:127], v143 offset:23552
	global_load_lds_dwordx4 v[146:147], off
	v_lshl_add_u64 v[146:147], v[212:213], 0, s[16:17]
	s_mov_b32 m0, s50
	s_addc_u32 s63, s31, 0
	global_load_lds_dwordx4 v[146:147], off
	v_lshl_add_u64 v[146:147], s[62:63], 0, v[132:133]
	s_mov_b32 m0, s51
	s_nop 0
	global_load_lds_dwordx4 v[146:147], off
	v_lshl_add_u64 v[146:147], s[62:63], 0, v[128:129]
	s_mov_b32 m0, s52
	s_nop 0
	global_load_lds_dwordx4 v[146:147], off
	v_lshl_add_u64 v[146:147], s[60:61], 0, v[134:135]
	s_mov_b32 m0, s23
	s_nop 0
	global_load_lds_dwordx4 v[146:147], off
	v_lshl_add_u64 v[146:147], s[60:61], 0, v[130:131]
	s_mov_b32 m0, s37
	s_nop 0
	global_load_lds_dwordx4 v[146:147], off
	s_waitcnt vmcnt(8)
	s_waitcnt lgkmcnt(0)
	s_barrier
; #define PG8_STAGE(bufoff, gbase, voff) do { _Pragma("unroll") for (int _i = 0; _i < 2; ++_i) \
;         __builtin_amdgcn_global_load_lds((const unsigned*)((const char*)(gbase) + (voff)[_i]), (PG8_LAS unsigned*)(lds + (bufoff) + ldsw + _i * 8192), 16, 0, 0); } while (0)
; #define PG8_LDA(dst, b, h) do { _Pragma("unroll") for (int m = 0; m < 4; ++m) _Pragma("unroll") for (int k = 0; k < 2; ++k) dst[m][k] = *(const PG8_LAS bf16x8*)(lds + PG8_SA(b, h) + aoff + m * 2048 + k * 1024); } while (0)
; #define PG8_LDB(dst, b, h) do { _Pragma("unroll") for (int n = 0; n < 2; ++n) _Pragma("unroll") for (int k = 0; k < 2; ++k) dst[n][k] = *(const PG8_LAS bf16x8*)(lds + PG8_SB(b, h) + boff + n * 2048 + k * 1024); } while (0)
; #define PG8_MMA(ai, bj, At, Bt) do { __builtin_amdgcn_s_setprio(1); _Pragma("unroll") for (int m = 0; m < 4; ++m) _Pragma("unroll") for (int n = 0; n < 2; ++n) _Pragma("unroll") for (int k = 0; k < 2; ++k) \
;         acc[ai][bj][m][n] = __builtin_amdgcn_mfma_f32_16x16x32_bf16(Bt[n][k], At[m][k], acc[ai][bj][m][n], 0, 0, 0); __builtin_amdgcn_s_setprio(0); } while (0)
; #define PG8_WAIT_V(n) asm volatile("s_waitcnt vmcnt(" #n ")" ::: "memory")
; #define PG8_WAIT_L(n) asm volatile("s_waitcnt lgkmcnt(" #n ")" ::: "memory")
; #define PG8_BAR __builtin_amdgcn_s_barrier()
; #define PG8_SCHED __builtin_amdgcn_sched_barrier(0)
;     ...
;             PG8_LDB(B0, 0, 0); PG8_LDB(B1, 0, 1); PG8_SCHED; PG8_LDA(At, 0, 0); PG8_STAGE(PG8_SA(1, 1), a1 + hstepA, voffA);
;             PG8_WAIT_V(8); PG8_WAIT_L(0); PG8_BAR; PG8_MMA(0, 0, At, B0); PG8_MMA(0, 1, At, B1); PG8_BAR; PG8_SCHED;
;             PG8_LDA(At, 0, 1); PG8_STAGE(PG8_SB(0, 0), b2, voffB); PG8_STAGE(PG8_SB(0, 1), b2 + hstepB, voffB); PG8_STAGE(PG8_SA(0, 0), a2, voffA);
;             PG8_WAIT_V(8); PG8_WAIT_L(0); PG8_BAR; PG8_MMA(1, 0, At, B0); PG8_MMA(1, 1, At, B1); PG8_BAR; PG8_SCHED;
;             PG8_LDB(B0, 1, 0); PG8_LDB(B1, 1, 1); PG8_SCHED; PG8_LDA(At, 1, 0); PG8_STAGE(PG8_SA(0, 1), a2 + hstepA, voffA);
;             PG8_WAIT_V(8); PG8_WAIT_L(0); PG8_BAR; PG8_MMA(0, 0, At, B0); PG8_MMA(0, 1, At, B1); PG8_BAR; PG8_SCHED;
;             PG8_LDA(At, 1, 1); PG8_STAGE(PG8_SB(1, 0), b3, voffB); PG8_STAGE(PG8_SB(1, 1), b3 + hstepB, voffB); PG8_STAGE(PG8_SA(1, 0), a3, voffA);
;             PG8_WAIT_V(8); PG8_WAIT_L(0); PG8_BAR; PG8_MMA(1, 0, At, B0); PG8_MMA(1, 1, At, B1); PG8_BAR; PG8_SCHED;
	s_setprio 1
	s_waitcnt lgkmcnt(0)
	v_mfma_f32_16x16x32_bf16 v[146:149], v[0:3], v[60:63], 0
	v_mfma_f32_16x16x32_bf16 v[154:157], v[0:3], v[104:107], 0
	v_mfma_f32_16x16x32_bf16 v[162:165], v[0:3], v[112:115], 0
	v_mfma_f32_16x16x32_bf16 v[0:3], v[0:3], v[120:123], 0
	v_mfma_f32_16x16x32_bf16 v[146:149], v[4:7], v[100:103], v[146:149]
	v_mfma_f32_16x16x32_bf16 v[154:157], v[4:7], v[108:111], v[154:157]
	v_mfma_f32_16x16x32_bf16 v[162:165], v[4:7], v[116:119], v[162:165]
	v_mfma_f32_16x16x32_bf16 v[0:3], v[4:7], v[124:127], v[0:3]
	v_mfma_f32_16x16x32_bf16 v[4:7], v[8:11], v[120:123], 0
	v_mfma_f32_16x16x32_bf16 v[150:153], v[8:11], v[60:63], 0
	v_mfma_f32_16x16x32_bf16 v[158:161], v[8:11], v[104:107], 0
	v_mfma_f32_16x16x32_bf16 v[166:169], v[8:11], v[112:115], 0
	v_mfma_f32_16x16x32_bf16 v[4:7], v[12:15], v[124:127], v[4:7]
	v_mfma_f32_16x16x32_bf16 v[150:153], v[12:15], v[100:103], v[150:153]
	v_mfma_f32_16x16x32_bf16 v[158:161], v[12:15], v[108:111], v[158:161]
	v_mfma_f32_16x16x32_bf16 v[166:169], v[12:15], v[116:119], v[166:169]
	s_setprio 0
	s_setprio 1
	v_mfma_f32_16x16x32_bf16 v[8:11], v[16:19], v[60:63], 0
	v_mfma_f32_16x16x32_bf16 v[12:15], v[24:27], v[60:63], 0
	v_mfma_f32_16x16x32_bf16 v[8:11], v[20:23], v[100:103], v[8:11]
	v_mfma_f32_16x16x32_bf16 v[12:15], v[28:31], v[100:103], v[12:15]
	v_mfma_f32_16x16x32_bf16 v[60:63], v[16:19], v[104:107], 0
	v_mfma_f32_16x16x32_bf16 v[100:103], v[24:27], v[104:107], 0
	v_mfma_f32_16x16x32_bf16 v[104:107], v[16:19], v[112:115], 0
	v_mfma_f32_16x16x32_bf16 v[16:19], v[16:19], v[120:123], 0
	v_mfma_f32_16x16x32_bf16 v[60:63], v[20:23], v[108:111], v[60:63]
	v_mfma_f32_16x16x32_bf16 v[100:103], v[28:31], v[108:111], v[100:103]
	v_mfma_f32_16x16x32_bf16 v[104:107], v[20:23], v[116:119], v[104:107]
	v_mfma_f32_16x16x32_bf16 v[108:111], v[24:27], v[112:115], 0
	s_setprio 2
	s_barrier
	v_mfma_f32_16x16x32_bf16 v[16:19], v[20:23], v[124:127], v[16:19]
	v_mfma_f32_16x16x32_bf16 v[20:23], v[24:27], v[120:123], 0
	v_mfma_f32_16x16x32_bf16 v[108:111], v[28:31], v[116:119], v[108:111]
	v_mfma_f32_16x16x32_bf16 v[20:23], v[28:31], v[124:127], v[20:23]
	s_setprio 0
	s_nop 0
	ds_read_b128 v[24:27], v144
	ds_read_b128 v[28:31], v144 offset:1024
	ds_read_b128 v[112:115], v144 offset:2048
	ds_read_b128 v[116:119], v144 offset:3072
	ds_read_b128 v[120:123], v145
	ds_read_b128 v[124:127], v145 offset:1024
	ds_read_b128 v[170:173], v145 offset:2048
	ds_read_b128 v[174:177], v145 offset:3072
	s_add_u32 s60, s26, 0x14000
	s_addc_u32 s61, s27, 0
	s_mov_b32 m0, s39
	v_lshl_add_u64 v[214:215], s[60:61], 0, v[134:135]
	ds_read_b128 v[178:181], v143 offset:32768
	ds_read_b128 v[182:185], v143 offset:33792
	ds_read_b128 v[186:189], v143 offset:34816
	ds_read_b128 v[190:193], v143 offset:35840
	ds_read_b128 v[194:197], v143 offset:36864
	ds_read_b128 v[198:201], v143 offset:37888
	ds_read_b128 v[202:205], v143 offset:38912
	ds_read_b128 v[206:209], v143 offset:39936
	global_load_lds_dwordx4 v[214:215], off
	v_lshl_add_u64 v[214:215], s[60:61], 0, v[130:131]
	s_mov_b32 m0, s40
	s_nop 0
	global_load_lds_dwordx4 v[214:215], off
	s_waitcnt vmcnt(8)
	s_waitcnt lgkmcnt(0)
	s_barrier
	s_setprio 1
	s_waitcnt lgkmcnt(0)
	v_mfma_f32_16x16x32_bf16 v[64:67], v[24:27], v[178:181], v[64:67]
	v_mfma_f32_16x16x32_bf16 v[68:71], v[112:115], v[178:181], v[68:71]
	v_mfma_f32_16x16x32_bf16 v[72:75], v[24:27], v[186:189], v[72:75]
	v_mfma_f32_16x16x32_bf16 v[76:79], v[112:115], v[186:189], v[76:79]
	v_mfma_f32_16x16x32_bf16 v[80:83], v[24:27], v[194:197], v[80:83]
	v_mfma_f32_16x16x32_bf16 v[84:87], v[112:115], v[194:197], v[84:87]
	v_mfma_f32_16x16x32_bf16 v[88:91], v[24:27], v[202:205], v[88:91]
	v_mfma_f32_16x16x32_bf16 v[92:95], v[112:115], v[202:205], v[92:95]
	v_mfma_f32_16x16x32_bf16 v[64:67], v[28:31], v[182:185], v[64:67]
	v_mfma_f32_16x16x32_bf16 v[68:71], v[116:119], v[182:185], v[68:71]
	v_mfma_f32_16x16x32_bf16 v[72:75], v[28:31], v[190:193], v[72:75]
	v_mfma_f32_16x16x32_bf16 v[76:79], v[116:119], v[190:193], v[76:79]
	v_mfma_f32_16x16x32_bf16 v[80:83], v[28:31], v[198:201], v[80:83]
	v_mfma_f32_16x16x32_bf16 v[84:87], v[116:119], v[198:201], v[84:87]
	v_mfma_f32_16x16x32_bf16 v[88:91], v[28:31], v[206:209], v[88:91]
	v_mfma_f32_16x16x32_bf16 v[92:95], v[116:119], v[206:209], v[92:95]
	s_setprio 0
	s_setprio 1
	v_mfma_f32_16x16x32_bf16 v[96:99], v[120:123], v[178:181], v[96:99]
	v_mfma_f32_16x16x32_bf16 v[32:35], v[170:173], v[178:181], v[32:35]
	v_mfma_f32_16x16x32_bf16 v[36:39], v[120:123], v[186:189], v[36:39]
	v_mfma_f32_16x16x32_bf16 v[40:43], v[170:173], v[186:189], v[40:43]
	v_mfma_f32_16x16x32_bf16 v[44:47], v[120:123], v[194:197], v[44:47]
	v_mfma_f32_16x16x32_bf16 v[48:51], v[170:173], v[194:197], v[48:51]
	v_mfma_f32_16x16x32_bf16 v[52:55], v[120:123], v[202:205], v[52:55]
	v_mfma_f32_16x16x32_bf16 v[56:59], v[170:173], v[202:205], v[56:59]
	v_mfma_f32_16x16x32_bf16 v[96:99], v[124:127], v[182:185], v[96:99]
	v_mfma_f32_16x16x32_bf16 v[32:35], v[174:177], v[182:185], v[32:35]
	v_mfma_f32_16x16x32_bf16 v[36:39], v[124:127], v[190:193], v[36:39]
	v_mfma_f32_16x16x32_bf16 v[40:43], v[174:177], v[190:193], v[40:43]
	s_setprio 2
	s_barrier
; #define PG8_STAGE(bufoff, gbase, voff) do { _Pragma("unroll") for (int _i = 0; _i < 2; ++_i) \
;         __builtin_amdgcn_global_load_lds((const unsigned*)((const char*)(gbase) + (voff)[_i]), (PG8_LAS unsigned*)(lds + (bufoff) + ldsw + _i * 8192), 16, 0, 0); } while (0)
; #define PG8_LDA(dst, b, h) do { _Pragma("unroll") for (int m = 0; m < 4; ++m) _Pragma("unroll") for (int k = 0; k < 2; ++k) dst[m][k] = *(const PG8_LAS bf16x8*)(lds + PG8_SA(b, h) + aoff + m * 2048 + k * 1024); } while (0)
; #define PG8_LDB(dst, b, h) do { _Pragma("unroll") for (int n = 0; n < 2; ++n) _Pragma("unroll") for (int k = 0; k < 2; ++k) dst[n][k] = *(const PG8_LAS bf16x8*)(lds + PG8_SB(b, h) + boff + n * 2048 + k * 1024); } while (0)
; #define PG8_MMA(ai, bj, At, Bt) do { __builtin_amdgcn_s_setprio(1); _Pragma("unroll") for (int m = 0; m < 4; ++m) _Pragma("unroll") for (int n = 0; n < 2; ++n) _Pragma("unroll") for (int k = 0; k < 2; ++k) \
;         acc[ai][bj][m][n] = __builtin_amdgcn_mfma_f32_16x16x32_bf16(Bt[n][k], At[m][k], acc[ai][bj][m][n], 0, 0, 0); __builtin_amdgcn_s_setprio(0); } while (0)
; #define PG8_WAIT_V(n) asm volatile("s_waitcnt vmcnt(" #n ")" ::: "memory")
; #define PG8_WAIT_L(n) asm volatile("s_waitcnt lgkmcnt(" #n ")" ::: "memory")
; #define PG8_BAR __builtin_amdgcn_s_barrier()
; #define PG8_SCHED __builtin_amdgcn_sched_barrier(0)
;     ...
;             PG8_LDB(B0, 0, 0); PG8_LDB(B1, 0, 1); PG8_SCHED; PG8_LDA(At, 0, 0); PG8_STAGE(PG8_SA(1, 1), a1 + hstepA, voffA);
;             PG8_WAIT_V(8); PG8_WAIT_L(0); PG8_BAR; PG8_MMA(0, 0, At, B0); PG8_MMA(0, 1, At, B1); PG8_BAR; PG8_SCHED;
;             PG8_LDA(At, 0, 1); PG8_STAGE(PG8_SB(0, 0), b2, voffB); PG8_STAGE(PG8_SB(0, 1), b2 + hstepB, voffB); PG8_STAGE(PG8_SA(0, 0), a2, voffA);
;             PG8_WAIT_V(8); PG8_WAIT_L(0); PG8_BAR; PG8_MMA(1, 0, At, B0); PG8_MMA(1, 1, At, B1); PG8_BAR; PG8_SCHED;
;             PG8_LDB(B0, 1, 0); PG8_LDB(B1, 1, 1); PG8_SCHED; PG8_LDA(At, 1, 0); PG8_STAGE(PG8_SA(0, 1), a2 + hstepA, voffA);
;             PG8_WAIT_V(8); PG8_WAIT_L(0); PG8_BAR; PG8_MMA(0, 0, At, B0); PG8_MMA(0, 1, At, B1); PG8_BAR; PG8_SCHED;
;             PG8_LDA(At, 1, 1); PG8_STAGE(PG8_SB(1, 0), b3, voffB); PG8_STAGE(PG8_SB(1, 1), b3 + hstepB, voffB); PG8_STAGE(PG8_SA(1, 0), a3, voffA);
;             PG8_WAIT_V(8); PG8_WAIT_L(0); PG8_BAR; PG8_MMA(1, 0, At, B0); PG8_MMA(1, 1, At, B1); PG8_BAR; PG8_SCHED;
	v_mfma_f32_16x16x32_bf16 v[44:47], v[124:127], v[198:201], v[44:47]
	v_mfma_f32_16x16x32_bf16 v[48:51], v[174:177], v[198:201], v[48:51]
	v_mfma_f32_16x16x32_bf16 v[52:55], v[124:127], v[206:209], v[52:55]
	v_mfma_f32_16x16x32_bf16 v[56:59], v[174:177], v[206:209], v[56:59]
	s_setprio 0
	s_nop 0
	s_mov_b32 m0, s53
	v_lshl_add_u64 v[210:211], v[210:211], 0, s[18:19]
	s_add_u32 s30, s30, 0x10180
	ds_read_b128 v[178:181], v143 offset:49152
	ds_read_b128 v[182:185], v143 offset:50176
	ds_read_b128 v[186:189], v143 offset:51200
	ds_read_b128 v[190:193], v143 offset:52224
	ds_read_b128 v[194:197], v143 offset:53248
	ds_read_b128 v[198:201], v143 offset:54272
	ds_read_b128 v[202:205], v143 offset:55296
	ds_read_b128 v[206:209], v143 offset:56320
	global_load_lds_dwordx4 v[210:211], off
	v_lshl_add_u64 v[210:211], v[212:213], 0, s[18:19]
	s_mov_b32 m0, s54
	s_addc_u32 s31, s31, 0
	global_load_lds_dwordx4 v[210:211], off
	v_lshl_add_u64 v[210:211], s[30:31], 0, v[132:133]
	s_mov_b32 m0, s55
	s_nop 0
	global_load_lds_dwordx4 v[210:211], off
	v_lshl_add_u64 v[210:211], s[30:31], 0, v[128:129]
	s_mov_b32 m0, s56
	s_nop 0
	global_load_lds_dwordx4 v[210:211], off
	v_lshl_add_u64 v[210:211], s[34:35], 0, v[134:135]
	s_mov_b32 m0, s42
	s_nop 0
	global_load_lds_dwordx4 v[210:211], off
	v_lshl_add_u64 v[210:211], s[34:35], 0, v[130:131]
	s_mov_b32 m0, s43
	s_nop 0
	global_load_lds_dwordx4 v[210:211], off
	s_waitcnt vmcnt(8)
	s_waitcnt lgkmcnt(0)
	s_barrier
	s_setprio 1
	s_waitcnt lgkmcnt(0)
	v_mfma_f32_16x16x32_bf16 v[0:3], v[24:27], v[202:205], v[0:3]
	v_mfma_f32_16x16x32_bf16 v[4:7], v[112:115], v[202:205], v[4:7]
	v_mfma_f32_16x16x32_bf16 v[146:149], v[24:27], v[178:181], v[146:149]
	v_mfma_f32_16x16x32_bf16 v[150:153], v[112:115], v[178:181], v[150:153]
	v_mfma_f32_16x16x32_bf16 v[154:157], v[24:27], v[186:189], v[154:157]
	v_mfma_f32_16x16x32_bf16 v[158:161], v[112:115], v[186:189], v[158:161]
	v_mfma_f32_16x16x32_bf16 v[162:165], v[24:27], v[194:197], v[162:165]
	v_mfma_f32_16x16x32_bf16 v[166:169], v[112:115], v[194:197], v[166:169]
	v_mfma_f32_16x16x32_bf16 v[0:3], v[28:31], v[206:209], v[0:3]
	v_mfma_f32_16x16x32_bf16 v[4:7], v[116:119], v[206:209], v[4:7]
	v_mfma_f32_16x16x32_bf16 v[146:149], v[28:31], v[182:185], v[146:149]
	v_mfma_f32_16x16x32_bf16 v[150:153], v[116:119], v[182:185], v[150:153]
	v_mfma_f32_16x16x32_bf16 v[154:157], v[28:31], v[190:193], v[154:157]
	v_mfma_f32_16x16x32_bf16 v[158:161], v[116:119], v[190:193], v[158:161]
	v_mfma_f32_16x16x32_bf16 v[162:165], v[28:31], v[198:201], v[162:165]
	v_mfma_f32_16x16x32_bf16 v[166:169], v[116:119], v[198:201], v[166:169]
	s_setprio 0
	s_setprio 1
	v_mfma_f32_16x16x32_bf16 v[8:11], v[120:123], v[178:181], v[8:11]
	v_mfma_f32_16x16x32_bf16 v[12:15], v[170:173], v[178:181], v[12:15]
	v_mfma_f32_16x16x32_bf16 v[24:27], v[120:123], v[186:189], v[60:63]
	v_mfma_f32_16x16x32_bf16 v[28:31], v[170:173], v[186:189], v[100:103]
	v_mfma_f32_16x16x32_bf16 v[60:63], v[120:123], v[194:197], v[104:107]
	v_mfma_f32_16x16x32_bf16 v[100:103], v[170:173], v[194:197], v[108:111]
	v_mfma_f32_16x16x32_bf16 v[16:19], v[120:123], v[202:205], v[16:19]
	v_mfma_f32_16x16x32_bf16 v[20:23], v[170:173], v[202:205], v[20:23]
	v_mfma_f32_16x16x32_bf16 v[8:11], v[124:127], v[182:185], v[8:11]
	v_mfma_f32_16x16x32_bf16 v[12:15], v[174:177], v[182:185], v[12:15]
	v_mfma_f32_16x16x32_bf16 v[24:27], v[124:127], v[190:193], v[24:27]
	v_mfma_f32_16x16x32_bf16 v[28:31], v[174:177], v[190:193], v[28:31]
	s_setprio 2
	s_barrier
	v_mfma_f32_16x16x32_bf16 v[60:63], v[124:127], v[198:201], v[60:63]
	v_mfma_f32_16x16x32_bf16 v[100:103], v[174:177], v[198:201], v[100:103]
	v_mfma_f32_16x16x32_bf16 v[16:19], v[124:127], v[206:209], v[16:19]
	v_mfma_f32_16x16x32_bf16 v[20:23], v[174:177], v[206:209], v[20:23]
	s_setprio 0
	s_nop 0
	ds_read_b128 v[104:107], v141
	ds_read_b128 v[108:111], v141 offset:1024
	ds_read_b128 v[112:115], v141 offset:2048
	ds_read_b128 v[116:119], v141 offset:3072
	ds_read_b128 v[120:123], v142
	ds_read_b128 v[124:127], v142 offset:1024
	ds_read_b128 v[170:173], v142 offset:2048
	ds_read_b128 v[174:177], v142 offset:3072
	s_add_u32 s30, s28, 0x8000
	s_addc_u32 s31, s29, 0
	s_add_u32 s26, s26, 0x1c000
	s_addc_u32 s27, s27, 0
	s_mov_b32 m0, s46
	v_lshl_add_u64 v[210:211], s[26:27], 0, v[134:135]
	ds_read_b128 v[178:181], v143
	ds_read_b128 v[182:185], v143 offset:1024
	ds_read_b128 v[186:189], v143 offset:2048
	ds_read_b128 v[190:193], v143 offset:3072
	ds_read_b128 v[194:197], v143 offset:4096
	ds_read_b128 v[198:201], v143 offset:5120
	ds_read_b128 v[202:205], v143 offset:6144
	ds_read_b128 v[206:209], v143 offset:7168
	global_load_lds_dwordx4 v[210:211], off
	v_lshl_add_u64 v[210:211], s[26:27], 0, v[130:131]
	s_mov_b32 m0, s47
	s_nop 0
	global_load_lds_dwordx4 v[210:211], off
	s_waitcnt vmcnt(8)
	s_waitcnt lgkmcnt(0)
	s_barrier
; #define PG8_STAGE(bufoff, gbase, voff) do { _Pragma("unroll") for (int _i = 0; _i < 2; ++_i) \
;         __builtin_amdgcn_global_load_lds((const unsigned*)((const char*)(gbase) + (voff)[_i]), (PG8_LAS unsigned*)(lds + (bufoff) + ldsw + _i * 8192), 16, 0, 0); } while (0)
; #define PG8_LDA(dst, b, h) do { _Pragma("unroll") for (int m = 0; m < 4; ++m) _Pragma("unroll") for (int k = 0; k < 2; ++k) dst[m][k] = *(const PG8_LAS bf16x8*)(lds + PG8_SA(b, h) + aoff + m * 2048 + k * 1024); } while (0)
; #define PG8_LDB(dst, b, h) do { _Pragma("unroll") for (int n = 0; n < 2; ++n) _Pragma("unroll") for (int k = 0; k < 2; ++k) dst[n][k] = *(const PG8_LAS bf16x8*)(lds + PG8_SB(b, h) + boff + n * 2048 + k * 1024); } while (0)
; #define PG8_WAIT_V(n) asm volatile("s_waitcnt vmcnt(" #n ")" ::: "memory")
; #define PG8_WAIT_L(n) asm volatile("s_waitcnt lgkmcnt(" #n ")" ::: "memory")
;     ...
;         for (int t = 0; t < nt; t += 2) {
;             const bool last = (t == nt - 2);
;             const char* a1 = cA + (ptrdiff_t)(t + 1) * kstepA;
;             const char* a2 = last ? nA : cA + (ptrdiff_t)(t + 2) * kstepA; const char* b2 = last ? nB : cB + (ptrdiff_t)(t + 2) * kstep;
;             const char* a3 = a2 + kstepA; const char* b3 = b2 + kstep;
;             if (last && has_next) S.a_ready(nxt);
;             if constexpr (SP2) {
;             PG8_LDB(B0, 0, 0); PG8_LDB(B1, 0, 1); PG8_SCHED; PG8_LDA(At, 0, 0); PG8_STAGE(PG8_SA(1, 1), a1 + hstepA, voffA);
;             PG8_WAIT_V(8); PG8_WAIT_L(0); PG8_BAR; PG8_MMA(0, 0, At, B0); PG8_MMA(0, 1, At, B1); PG8_BAR; PG8_SCHED;
;             PG8_LDA(At, 0, 1); PG8_STAGE(PG8_SB(0, 0), b2, voffB); PG8_STAGE(PG8_SB(0, 1), b2 + hstepB, voffB); PG8_STAGE(PG8_SA(0, 0), a2, voffA);
;             PG8_WAIT_V(8); PG8_WAIT_L(0); PG8_BAR; PG8_MMA(1, 0, At, B0); PG8_MMA(1, 1, At, B1); PG8_BAR; PG8_SCHED;
;             PG8_LDB(B0, 1, 0); PG8_LDB(B1, 1, 1); PG8_SCHED; PG8_LDA(At, 1, 0); PG8_STAGE(PG8_SA(0, 1), a2 + hstepA, voffA);
;             PG8_WAIT_V(8); PG8_WAIT_L(0); PG8_BAR; PG8_MMA(0, 0, At, B0); PG8_MMA(0, 1, At, B1); PG8_BAR; PG8_SCHED;
;             PG8_LDA(At, 1, 1); PG8_STAGE(PG8_SB(1, 0), b3, voffB); PG8_STAGE(PG8_SB(1, 1), b3 + hstepB, voffB); PG8_STAGE(PG8_SA(1, 0), a3, voffA);
;             PG8_WAIT_V(8); PG8_WAIT_L(0); PG8_BAR; PG8_MMA(1, 0, At, B0); PG8_MMA(1, 1, At, B1); PG8_BAR; PG8_SCHED;
	s_setprio 1
	s_waitcnt lgkmcnt(0)
	v_mfma_f32_16x16x32_bf16 v[64:67], v[104:107], v[178:181], v[64:67]
	v_mfma_f32_16x16x32_bf16 v[68:71], v[112:115], v[178:181], v[68:71]
	v_mfma_f32_16x16x32_bf16 v[72:75], v[104:107], v[186:189], v[72:75]
	v_mfma_f32_16x16x32_bf16 v[76:79], v[112:115], v[186:189], v[76:79]
	v_mfma_f32_16x16x32_bf16 v[80:83], v[104:107], v[194:197], v[80:83]
	v_mfma_f32_16x16x32_bf16 v[84:87], v[112:115], v[194:197], v[84:87]
	v_mfma_f32_16x16x32_bf16 v[88:91], v[104:107], v[202:205], v[88:91]
	v_mfma_f32_16x16x32_bf16 v[64:67], v[108:111], v[182:185], v[64:67]
	v_mfma_f32_16x16x32_bf16 v[68:71], v[116:119], v[182:185], v[68:71]
	v_mfma_f32_16x16x32_bf16 v[72:75], v[108:111], v[190:193], v[72:75]
	v_mfma_f32_16x16x32_bf16 v[76:79], v[116:119], v[190:193], v[76:79]
	v_mfma_f32_16x16x32_bf16 v[80:83], v[108:111], v[198:201], v[80:83]
	v_mfma_f32_16x16x32_bf16 v[84:87], v[116:119], v[198:201], v[84:87]
	v_mfma_f32_16x16x32_bf16 v[210:213], v[108:111], v[206:209], v[88:91]
	v_mfma_f32_16x16x32_bf16 v[88:91], v[112:115], v[202:205], v[92:95]
	v_mfma_f32_16x16x32_bf16 v[214:217], v[116:119], v[206:209], v[88:91]
	s_setprio 0
	s_setprio 1
	v_mfma_f32_16x16x32_bf16 v[88:91], v[120:123], v[178:181], v[96:99]
	v_mfma_f32_16x16x32_bf16 v[32:35], v[170:173], v[178:181], v[32:35]
	v_mfma_f32_16x16x32_bf16 v[36:39], v[120:123], v[186:189], v[36:39]
	v_mfma_f32_16x16x32_bf16 v[40:43], v[170:173], v[186:189], v[40:43]
	v_mfma_f32_16x16x32_bf16 v[44:47], v[120:123], v[194:197], v[44:47]
	v_mfma_f32_16x16x32_bf16 v[48:51], v[170:173], v[194:197], v[48:51]
	v_mfma_f32_16x16x32_bf16 v[52:55], v[120:123], v[202:205], v[52:55]
	v_mfma_f32_16x16x32_bf16 v[56:59], v[170:173], v[202:205], v[56:59]
	v_mfma_f32_16x16x32_bf16 v[96:99], v[124:127], v[182:185], v[88:91]
	v_mfma_f32_16x16x32_bf16 v[32:35], v[174:177], v[182:185], v[32:35]
	v_mfma_f32_16x16x32_bf16 v[36:39], v[124:127], v[190:193], v[36:39]
	v_mfma_f32_16x16x32_bf16 v[40:43], v[174:177], v[190:193], v[40:43]
	s_setprio 2
	s_barrier
	v_mfma_f32_16x16x32_bf16 v[44:47], v[124:127], v[198:201], v[44:47]
	v_mfma_f32_16x16x32_bf16 v[48:51], v[174:177], v[198:201], v[48:51]
	v_mfma_f32_16x16x32_bf16 v[52:55], v[124:127], v[206:209], v[52:55]
	v_mfma_f32_16x16x32_bf16 v[56:59], v[174:177], v[206:209], v[56:59]
	s_setprio 0
	s_nop 0
	s_mov_b32 m0, s48
	v_lshl_add_u64 v[246:247], s[24:25], 0, v[132:133]
	s_add_u32 s26, s24, 0x10000
	ds_read_b128 v[88:91], v143 offset:16384
	ds_read_b128 v[92:95], v143 offset:17408
	ds_read_b128 v[178:181], v143 offset:18432
	ds_read_b128 v[182:185], v143 offset:19456
	ds_read_b128 v[186:189], v143 offset:20480
	ds_read_b128 v[190:193], v143 offset:21504
	ds_read_b128 v[194:197], v143 offset:22528
	ds_read_b128 v[198:201], v143 offset:23552
	global_load_lds_dwordx4 v[246:247], off
	v_lshl_add_u64 v[248:249], s[24:25], 0, v[128:129]
	s_mov_b32 m0, s50
	s_addc_u32 s27, s25, 0
	global_load_lds_dwordx4 v[248:249], off
	v_lshl_add_u64 v[202:203], s[26:27], 0, v[132:133]
	s_mov_b32 m0, s51
	s_nop 0
	global_load_lds_dwordx4 v[202:203], off
	v_lshl_add_u64 v[202:203], s[26:27], 0, v[128:129]
	s_mov_b32 m0, s52
	s_nop 0
	global_load_lds_dwordx4 v[202:203], off
	v_lshl_add_u64 v[202:203], s[28:29], 0, v[134:135]
	s_mov_b32 m0, s23
	s_nop 0
	global_load_lds_dwordx4 v[202:203], off
	v_lshl_add_u64 v[202:203], s[28:29], 0, v[130:131]
	s_mov_b32 m0, s37
	s_nop 0
	global_load_lds_dwordx4 v[202:203], off
	s_waitcnt vmcnt(8)
	s_waitcnt lgkmcnt(0)
	s_barrier
	s_setprio 1
	s_waitcnt lgkmcnt(0)
	v_mfma_f32_16x16x32_bf16 v[0:3], v[104:107], v[194:197], v[0:3]
	v_mfma_f32_16x16x32_bf16 v[4:7], v[112:115], v[194:197], v[4:7]
	v_mfma_f32_16x16x32_bf16 v[146:149], v[104:107], v[88:91], v[146:149]
	v_mfma_f32_16x16x32_bf16 v[150:153], v[112:115], v[88:91], v[150:153]
	v_mfma_f32_16x16x32_bf16 v[154:157], v[104:107], v[178:181], v[154:157]
	v_mfma_f32_16x16x32_bf16 v[158:161], v[112:115], v[178:181], v[158:161]
	v_mfma_f32_16x16x32_bf16 v[162:165], v[104:107], v[186:189], v[162:165]
	v_mfma_f32_16x16x32_bf16 v[166:169], v[112:115], v[186:189], v[166:169]
	v_mfma_f32_16x16x32_bf16 v[0:3], v[108:111], v[198:201], v[0:3]
	v_mfma_f32_16x16x32_bf16 v[4:7], v[116:119], v[198:201], v[4:7]
	v_mfma_f32_16x16x32_bf16 v[146:149], v[108:111], v[92:95], v[146:149]
	v_mfma_f32_16x16x32_bf16 v[150:153], v[116:119], v[92:95], v[150:153]
	v_mfma_f32_16x16x32_bf16 v[154:157], v[108:111], v[182:185], v[154:157]
	v_mfma_f32_16x16x32_bf16 v[158:161], v[116:119], v[182:185], v[158:161]
	v_mfma_f32_16x16x32_bf16 v[162:165], v[108:111], v[190:193], v[162:165]
	v_mfma_f32_16x16x32_bf16 v[166:169], v[116:119], v[190:193], v[166:169]
	s_setprio 0
	s_setprio 1
	v_mfma_f32_16x16x32_bf16 v[8:11], v[120:123], v[88:91], v[8:11]
	v_mfma_f32_16x16x32_bf16 v[202:205], v[124:127], v[92:95], v[8:11]
	v_mfma_f32_16x16x32_bf16 v[8:11], v[170:173], v[88:91], v[12:15]
	v_mfma_f32_16x16x32_bf16 v[206:209], v[174:177], v[92:95], v[8:11]
	v_mfma_f32_16x16x32_bf16 v[8:11], v[120:123], v[178:181], v[24:27]
	v_mfma_f32_16x16x32_bf16 v[218:221], v[124:127], v[182:185], v[8:11]
	v_mfma_f32_16x16x32_bf16 v[8:11], v[170:173], v[178:181], v[28:31]
	v_mfma_f32_16x16x32_bf16 v[178:181], v[174:177], v[182:185], v[8:11]
	v_mfma_f32_16x16x32_bf16 v[8:11], v[120:123], v[186:189], v[60:63]
	v_mfma_f32_16x16x32_bf16 v[182:185], v[124:127], v[190:193], v[8:11]
	v_mfma_f32_16x16x32_bf16 v[8:11], v[170:173], v[186:189], v[100:103]
	v_mfma_f32_16x16x32_bf16 v[186:189], v[174:177], v[190:193], v[8:11]
	s_setprio 2
	s_barrier
;     ...
;             PG8_LDB(B0, 0, 0); PG8_LDB(B1, 0, 1); PG8_SCHED; PG8_LDA(At, 0, 0); PG8_STAGE(PG8_SA(1, 1), a1 + hstepA, voffA);
;             PG8_WAIT_V(8); PG8_WAIT_L(0); PG8_BAR; PG8_MMA(0, 0, At, B0); PG8_MMA(0, 1, At, B1); PG8_BAR; PG8_SCHED;
;             PG8_LDA(At, 0, 1); PG8_STAGE(PG8_SB(0, 0), b2, voffB); PG8_STAGE(PG8_SB(0, 1), b2 + hstepB, voffB); PG8_STAGE(PG8_SA(0, 0), a2, voffA);
;             PG8_WAIT_V(8); PG8_WAIT_L(0); PG8_BAR; PG8_MMA(1, 0, At, B0); PG8_MMA(1, 1, At, B1); PG8_BAR; PG8_SCHED;
;             PG8_LDB(B0, 1, 0); PG8_LDB(B1, 1, 1); PG8_SCHED; PG8_LDA(At, 1, 0); PG8_STAGE(PG8_SA(0, 1), a2 + hstepA, voffA);
;             PG8_WAIT_V(8); PG8_WAIT_L(0); PG8_BAR; PG8_MMA(0, 0, At, B0); PG8_MMA(0, 1, At, B1); PG8_BAR; PG8_SCHED;
;             PG8_LDA(At, 1, 1); PG8_STAGE(PG8_SB(1, 0), b3, voffB); PG8_STAGE(PG8_SB(1, 1), b3 + hstepB, voffB); PG8_STAGE(PG8_SA(1, 0), a3, voffA);
;             PG8_WAIT_V(8); PG8_WAIT_L(0); PG8_BAR; PG8_MMA(1, 0, At, B0); PG8_MMA(1, 1, At, B1); PG8_BAR; PG8_SCHED;
;             } else {
;             PG8_LDB(B0, 0, 0); PG8_SCHED; PG8_LDA(At, 0, 0); PG8_STAGE(PG8_SA(1, 1), a1 + hstepA, voffA);
;             PG8_WAIT_L(8); PG8_BAR; PG8_WAIT_L(0); PG8_MMA(0, 0, At, B0); PG8_BAR; PG8_SCHED;
;             PG8_LDB(B1, 0, 1); PG8_STAGE(PG8_SB(0, 0), b2, voffB);
;             PG8_BAR; PG8_WAIT_L(0); PG8_MMA(0, 1, At, B1); PG8_BAR;
;             PG8_LDA(At, 0, 1); PG8_STAGE(PG8_SA(0, 0), a2, voffA);
;             PG8_BAR; PG8_WAIT_L(0); PG8_MMA(1, 0, At, B0); PG8_BAR; PG8_SCHED;
;             PG8_STAGE(PG8_SB(0, 1), b2 + hstepB, voffB);
;             PG8_WAIT_V(6); PG8_BAR; PG8_MMA(1, 1, At, B1); PG8_BAR;
;             PG8_LDB(B0, 1, 0); PG8_SCHED; PG8_LDA(At, 1, 0); PG8_STAGE(PG8_SA(0, 1), a2 + hstepA, voffA);
;             PG8_WAIT_L(8); PG8_BAR; PG8_WAIT_L(0); PG8_MMA(0, 0, At, B0); PG8_BAR; PG8_SCHED;
;             PG8_LDB(B1, 1, 1); PG8_STAGE(PG8_SB(1, 0), b3, voffB);
;             PG8_BAR; PG8_WAIT_L(0); PG8_MMA(0, 1, At, B1); PG8_BAR;
;             PG8_LDA(At, 1, 1); PG8_STAGE(PG8_SA(1, 0), a3, voffA);
;             PG8_BAR; PG8_WAIT_L(0); PG8_MMA(1, 0, At, B0); PG8_BAR; PG8_SCHED;
;             PG8_STAGE(PG8_SB(1, 1), b3 + hstepB, voffB);
;             PG8_WAIT_V(6); PG8_BAR; PG8_MMA(1, 1, At, B1); PG8_BAR;
;             }
;         }
;         if constexpr (ALIGN_EPI) { if (wr == 0) PG8_BAR; }
	v_mfma_f32_16x16x32_bf16 v[8:11], v[120:123], v[194:197], v[16:19]
	v_mfma_f32_16x16x32_bf16 v[190:193], v[124:127], v[198:201], v[8:11]
	v_mfma_f32_16x16x32_bf16 v[8:11], v[170:173], v[194:197], v[20:23]
	v_mfma_f32_16x16x32_bf16 v[170:173], v[174:177], v[198:201], v[8:11]
	s_setprio 0
	s_nop 0
	s_nop 4
	ds_read_b128 v[8:11], v144
	ds_read_b128 v[12:15], v144 offset:1024
	ds_read_b128 v[16:19], v144 offset:2048
	ds_read_b128 v[20:23], v144 offset:3072
	ds_read_b128 v[174:177], v145
	ds_read_b128 v[194:197], v145 offset:1024
	ds_read_b128 v[198:201], v145 offset:2048
	ds_read_b128 v[222:225], v145 offset:3072
	s_add_u32 s26, s28, 0x4000
	s_addc_u32 s27, s29, 0
	s_mov_b32 m0, s39
	v_lshl_add_u64 v[88:89], s[26:27], 0, v[134:135]
	ds_read_b128 v[24:27], v143 offset:32768
	ds_read_b128 v[28:31], v143 offset:33792
	ds_read_b128 v[60:63], v143 offset:34816
	ds_read_b128 v[226:229], v143 offset:35840
	ds_read_b128 v[230:233], v143 offset:36864
	ds_read_b128 v[234:237], v143 offset:37888
	ds_read_b128 v[238:241], v143 offset:38912
	ds_read_b128 v[242:245], v143 offset:39936
	global_load_lds_dwordx4 v[88:89], off
	v_lshl_add_u64 v[88:89], s[26:27], 0, v[130:131]
	s_mov_b32 m0, s40
	s_nop 0
	global_load_lds_dwordx4 v[88:89], off
	s_waitcnt vmcnt(8)
	s_waitcnt lgkmcnt(0)
	s_barrier
	s_setprio 1
	s_waitcnt lgkmcnt(0)
	v_mfma_f32_16x16x32_bf16 v[64:67], v[8:11], v[24:27], v[64:67]
	v_mfma_f32_16x16x32_bf16 v[124:127], v[12:15], v[28:31], v[64:67]
	v_mfma_f32_16x16x32_bf16 v[64:67], v[16:19], v[24:27], v[68:71]
	v_mfma_f32_16x16x32_bf16 v[120:123], v[20:23], v[28:31], v[64:67]
	v_mfma_f32_16x16x32_bf16 v[64:67], v[8:11], v[60:63], v[72:75]
	v_mfma_f32_16x16x32_bf16 v[108:111], v[12:15], v[226:229], v[64:67]
	v_mfma_f32_16x16x32_bf16 v[64:67], v[16:19], v[60:63], v[76:79]
	v_mfma_f32_16x16x32_bf16 v[104:107], v[20:23], v[226:229], v[64:67]
	v_mfma_f32_16x16x32_bf16 v[64:67], v[8:11], v[230:233], v[80:83]
	v_mfma_f32_16x16x32_bf16 v[92:95], v[12:15], v[234:237], v[64:67]
	v_mfma_f32_16x16x32_bf16 v[64:67], v[16:19], v[230:233], v[84:87]
	v_mfma_f32_16x16x32_bf16 v[88:91], v[20:23], v[234:237], v[64:67]
	v_mfma_f32_16x16x32_bf16 v[64:67], v[8:11], v[238:241], v[210:213]
	v_mfma_f32_16x16x32_bf16 v[76:79], v[12:15], v[242:245], v[64:67]
	v_mfma_f32_16x16x32_bf16 v[64:67], v[16:19], v[238:241], v[214:217]
	v_mfma_f32_16x16x32_bf16 v[72:75], v[20:23], v[242:245], v[64:67]
	s_setprio 0
	s_setprio 1
	v_mfma_f32_16x16x32_bf16 v[64:67], v[174:177], v[24:27], v[96:99]
	v_mfma_f32_16x16x32_bf16 v[24:27], v[198:201], v[24:27], v[32:35]
	v_mfma_f32_16x16x32_bf16 v[112:115], v[222:225], v[28:31], v[24:27]
	v_mfma_f32_16x16x32_bf16 v[24:27], v[174:177], v[60:63], v[36:39]
	v_mfma_f32_16x16x32_bf16 v[100:103], v[194:197], v[226:229], v[24:27]
	v_mfma_f32_16x16x32_bf16 v[24:27], v[198:201], v[60:63], v[40:43]
	v_mfma_f32_16x16x32_bf16 v[96:99], v[222:225], v[226:229], v[24:27]
	v_mfma_f32_16x16x32_bf16 v[24:27], v[174:177], v[230:233], v[44:47]
	v_mfma_f32_16x16x32_bf16 v[84:87], v[194:197], v[234:237], v[24:27]
	v_mfma_f32_16x16x32_bf16 v[24:27], v[198:201], v[230:233], v[48:51]
	v_mfma_f32_16x16x32_bf16 v[80:83], v[222:225], v[234:237], v[24:27]
	v_mfma_f32_16x16x32_bf16 v[24:27], v[174:177], v[238:241], v[52:55]
	s_setprio 2
	s_barrier
	v_mfma_f32_16x16x32_bf16 v[60:63], v[194:197], v[242:245], v[24:27]
	v_mfma_f32_16x16x32_bf16 v[24:27], v[198:201], v[238:241], v[56:59]
	v_mfma_f32_16x16x32_bf16 v[116:119], v[194:197], v[28:31], v[64:67]
	v_mfma_f32_16x16x32_bf16 v[56:59], v[222:225], v[242:245], v[24:27]
	s_setprio 0
	s_nop 0
	s_mov_b32 m0, s53
	s_nop 2
	v_lshl_add_u64 v[24:25], v[246:247], 0, s[12:13]
	s_add_u32 s24, s24, 0x10080
	ds_read_b128 v[32:35], v143 offset:49152
	ds_read_b128 v[36:39], v143 offset:50176
	ds_read_b128 v[210:213], v143 offset:51200
	ds_read_b128 v[214:217], v143 offset:52224
	ds_read_b128 v[226:229], v143 offset:53248
	ds_read_b128 v[230:233], v143 offset:54272
	ds_read_b128 v[234:237], v143 offset:55296
	ds_read_b128 v[238:241], v143 offset:56320
	global_load_lds_dwordx4 v[24:25], off
	v_lshl_add_u64 v[24:25], v[248:249], 0, s[12:13]
	s_mov_b32 m0, s54
	s_addc_u32 s25, s25, 0
	global_load_lds_dwordx4 v[24:25], off
	v_lshl_add_u64 v[24:25], s[24:25], 0, v[132:133]
	s_mov_b32 m0, s55
	s_nop 0
	global_load_lds_dwordx4 v[24:25], off
	v_lshl_add_u64 v[24:25], s[24:25], 0, v[128:129]
	s_mov_b32 m0, s56
	s_nop 0
	global_load_lds_dwordx4 v[24:25], off
	v_lshl_add_u64 v[24:25], s[30:31], 0, v[134:135]
	s_mov_b32 m0, s42
	s_nop 0
	global_load_lds_dwordx4 v[24:25], off
	v_lshl_add_u64 v[24:25], s[30:31], 0, v[130:131]
	s_mov_b32 m0, s43
	s_nop 0
	global_load_lds_dwordx4 v[24:25], off
	s_waitcnt vmcnt(8)
	s_waitcnt lgkmcnt(0)
	s_barrier
	s_setprio 1
	s_waitcnt lgkmcnt(0)
	v_mfma_f32_16x16x32_bf16 v[24:27], v[8:11], v[32:35], v[146:149]
	v_mfma_f32_16x16x32_bf16 v[68:71], v[12:15], v[36:39], v[24:27]
	v_mfma_f32_16x16x32_bf16 v[24:27], v[16:19], v[32:35], v[150:153]
	v_mfma_f32_16x16x32_bf16 v[64:67], v[20:23], v[36:39], v[24:27]
	v_mfma_f32_16x16x32_bf16 v[24:27], v[8:11], v[210:213], v[154:157]
	v_mfma_f32_16x16x32_bf16 v[44:47], v[12:15], v[214:217], v[24:27]
	v_mfma_f32_16x16x32_bf16 v[24:27], v[16:19], v[210:213], v[158:161]
	v_mfma_f32_16x16x32_bf16 v[40:43], v[20:23], v[214:217], v[24:27]
	v_mfma_f32_16x16x32_bf16 v[24:27], v[8:11], v[226:229], v[162:165]
	v_mfma_f32_16x16x32_bf16 v[0:3], v[8:11], v[234:237], v[0:3]
	v_mfma_f32_16x16x32_bf16 v[28:31], v[12:15], v[230:233], v[24:27]
	v_mfma_f32_16x16x32_bf16 v[24:27], v[16:19], v[226:229], v[166:169]
	v_mfma_f32_16x16x32_bf16 v[12:15], v[12:15], v[238:241], v[0:3]
	v_mfma_f32_16x16x32_bf16 v[0:3], v[16:19], v[234:237], v[4:7]
	v_mfma_f32_16x16x32_bf16 v[24:27], v[20:23], v[230:233], v[24:27]
	v_mfma_f32_16x16x32_bf16 v[8:11], v[20:23], v[238:241], v[0:3]
	s_setprio 0
	s_setprio 1
	v_mfma_f32_16x16x32_bf16 v[0:3], v[174:177], v[32:35], v[202:205]
	v_mfma_f32_16x16x32_bf16 v[52:55], v[194:197], v[36:39], v[0:3]
	v_mfma_f32_16x16x32_bf16 v[0:3], v[198:201], v[32:35], v[206:209]
	v_mfma_f32_16x16x32_bf16 v[48:51], v[222:225], v[36:39], v[0:3]
	v_mfma_f32_16x16x32_bf16 v[0:3], v[174:177], v[210:213], v[218:221]
	v_mfma_f32_16x16x32_bf16 v[36:39], v[194:197], v[214:217], v[0:3]
	v_mfma_f32_16x16x32_bf16 v[0:3], v[198:201], v[210:213], v[178:181]
	v_mfma_f32_16x16x32_bf16 v[32:35], v[222:225], v[214:217], v[0:3]
	v_mfma_f32_16x16x32_bf16 v[0:3], v[174:177], v[226:229], v[182:185]
	v_mfma_f32_16x16x32_bf16 v[20:23], v[194:197], v[230:233], v[0:3]
	v_mfma_f32_16x16x32_bf16 v[0:3], v[198:201], v[226:229], v[186:189]
	v_mfma_f32_16x16x32_bf16 v[16:19], v[222:225], v[230:233], v[0:3]
	s_setprio 2
	s_barrier
	v_mfma_f32_16x16x32_bf16 v[0:3], v[174:177], v[234:237], v[190:193]
	v_mfma_f32_16x16x32_bf16 v[4:7], v[194:197], v[238:241], v[0:3]
	v_mfma_f32_16x16x32_bf16 v[0:3], v[198:201], v[234:237], v[170:173]
	v_mfma_f32_16x16x32_bf16 v[0:3], v[222:225], v[238:241], v[0:3]
	s_setprio 0
	s_nop 0
	s_and_b64 vcc, exec, s[0:1]
	s_cbranch_vccnz .LBB0_99
	s_barrier

; #define PG8_STAGE(bufoff, gbase, voff) do { _Pragma("unroll") for (int _i = 0; _i < 2; ++_i) \
;         __builtin_amdgcn_global_load_lds((const unsigned*)((const char*)(gbase) + (voff)[_i]), (PG8_LAS unsigned*)(lds + (bufoff) + ldsw + _i * 8192), 16, 0, 0); } while (0)
; #define PG8_LDA(dst, b, h) do { _Pragma("unroll") for (int m = 0; m < 4; ++m) _Pragma("unroll") for (int k = 0; k < 2; ++k) dst[m][k] = *(const PG8_LAS bf16x8*)(lds + PG8_SA(b, h) + aoff + m * 2048 + k * 1024); } while (0)
; #define PG8_LDB(dst, b, h) do { _Pragma("unroll") for (int n = 0; n < 2; ++n) _Pragma("unroll") for (int k = 0; k < 2; ++k) dst[n][k] = *(const PG8_LAS bf16x8*)(lds + PG8_SB(b, h) + boff + n * 2048 + k * 1024); } while (0)
; #define PG8_WAIT_V(n) asm volatile("s_waitcnt vmcnt(" #n ")" ::: "memory")
; #define PG8_WAIT_L(n) asm volatile("s_waitcnt lgkmcnt(" #n ")" ::: "memory")
;     ...
;         for (int t = 0; t < nt; t += 2) {
;             const bool last = (t == nt - 2);
;             const char* a1 = cA + (ptrdiff_t)(t + 1) * kstepA;
;             const char* a2 = last ? nA : cA + (ptrdiff_t)(t + 2) * kstepA; const char* b2 = last ? nB : cB + (ptrdiff_t)(t + 2) * kstep;
;             const char* a3 = a2 + kstepA; const char* b3 = b2 + kstep;
;             if (last && has_next) S.a_ready(nxt);
;             if constexpr (SP2) {
;             PG8_LDB(B0, 0, 0); PG8_LDB(B1, 0, 1); PG8_SCHED; PG8_LDA(At, 0, 0); PG8_STAGE(PG8_SA(1, 1), a1 + hstepA, voffA);
;             PG8_WAIT_V(8); PG8_WAIT_L(0); PG8_BAR; PG8_MMA(0, 0, At, B0); PG8_MMA(0, 1, At, B1); PG8_BAR; PG8_SCHED;
;             PG8_LDA(At, 0, 1); PG8_STAGE(PG8_SB(0, 0), b2, voffB); PG8_STAGE(PG8_SB(0, 1), b2 + hstepB, voffB); PG8_STAGE(PG8_SA(0, 0), a2, voffA);
;             PG8_WAIT_V(8); PG8_WAIT_L(0); PG8_BAR; PG8_MMA(1, 0, At, B0); PG8_MMA(1, 1, At, B1); PG8_BAR; PG8_SCHED;
;             PG8_LDB(B0, 1, 0); PG8_LDB(B1, 1, 1); PG8_SCHED; PG8_LDA(At, 1, 0); PG8_STAGE(PG8_SA(0, 1), a2 + hstepA, voffA);
;             PG8_WAIT_V(8); PG8_WAIT_L(0); PG8_BAR; PG8_MMA(0, 0, At, B0); PG8_MMA(0, 1, At, B1); PG8_BAR; PG8_SCHED;
;             PG8_LDA(At, 1, 1); PG8_STAGE(PG8_SB(1, 0), b3, voffB); PG8_STAGE(PG8_SB(1, 1), b3 + hstepB, voffB); PG8_STAGE(PG8_SA(1, 0), a3, voffA);
;             PG8_WAIT_V(8); PG8_WAIT_L(0); PG8_BAR; PG8_MMA(1, 0, At, B0); PG8_MMA(1, 1, At, B1); PG8_BAR; PG8_SCHED;
.LBB0_328:
	s_add_u32 s65, s6, 0x4000
	s_addc_u32 s66, s7, 0
	s_cmp_eq_u32 vcc_lo, 28
	s_cselect_b32 s90, s54, s65
	s_cselect_b32 s91, s29, s66
	s_cselect_b32 s88, s55, s56
	s_cselect_b32 s89, s31, s57
	s_add_u32 s86, s90, 0x8000
	s_addc_u32 s87, s91, 0
	s_add_i32 s65, 0, 0x10000
	s_add_i32 s66, 0, 0x14000
	v_add_u32_e32 v22, s65, v182
	v_add_u32_e32 v54, s66, v182
	ds_read_b128 v[10:13], v22
	ds_read_b128 v[14:17], v22 offset:1024
	ds_read_b128 v[18:21], v22 offset:2048
	ds_read_b128 v[22:25], v22 offset:3072
	ds_read_b128 v[26:29], v54
	ds_read_b128 v[38:41], v54 offset:1024
	ds_read_b128 v[50:53], v54 offset:2048
	ds_read_b128 v[54:57], v54 offset:3072
	v_lshl_add_u64 v[208:209], s[6:7], 0, v[168:169]
	s_add_i32 m0, s51, 0xc000
	ds_read_b128 v[172:175], v183
	ds_read_b128 v[176:179], v183 offset:1024
	ds_read_b128 v[184:187], v183 offset:2048
	ds_read_b128 v[188:191], v183 offset:3072
	ds_read_b128 v[192:195], v183 offset:4096
	ds_read_b128 v[196:199], v183 offset:5120
	ds_read_b128 v[200:203], v183 offset:6144
	ds_read_b128 v[204:207], v183 offset:7168
	global_load_lds_dwordx4 v[208:209], off
	v_lshl_add_u64 v[208:209], s[6:7], 0, v[170:171]
	s_add_i32 m0, s51, 0xe000
	s_nop 0
	global_load_lds_dwordx4 v[208:209], off
	s_waitcnt vmcnt(8)
	s_waitcnt lgkmcnt(0)
	s_barrier
	s_setprio 1
	s_waitcnt lgkmcnt(0)
	v_mfma_f32_16x16x32_bf16 v[158:161], v[10:13], v[172:175], v[158:161]
	v_mfma_f32_16x16x32_bf16 v[154:157], v[18:21], v[172:175], v[154:157]
	v_mfma_f32_16x16x32_bf16 v[142:145], v[10:13], v[184:187], v[142:145]
	v_mfma_f32_16x16x32_bf16 v[138:141], v[18:21], v[184:187], v[138:141]
	v_mfma_f32_16x16x32_bf16 v[126:129], v[10:13], v[192:195], v[126:129]
	v_mfma_f32_16x16x32_bf16 v[122:125], v[18:21], v[192:195], v[122:125]
	v_mfma_f32_16x16x32_bf16 v[110:113], v[10:13], v[200:203], v[110:113]
	v_mfma_f32_16x16x32_bf16 v[106:109], v[18:21], v[200:203], v[106:109]
	v_mfma_f32_16x16x32_bf16 v[158:161], v[14:17], v[176:179], v[158:161]
	v_mfma_f32_16x16x32_bf16 v[154:157], v[22:25], v[176:179], v[154:157]
	v_mfma_f32_16x16x32_bf16 v[142:145], v[14:17], v[188:191], v[142:145]
	v_mfma_f32_16x16x32_bf16 v[138:141], v[22:25], v[188:191], v[138:141]
	v_mfma_f32_16x16x32_bf16 v[126:129], v[14:17], v[196:199], v[126:129]
	v_mfma_f32_16x16x32_bf16 v[122:125], v[22:25], v[196:199], v[122:125]
	v_mfma_f32_16x16x32_bf16 v[110:113], v[14:17], v[204:207], v[110:113]
	v_mfma_f32_16x16x32_bf16 v[106:109], v[22:25], v[204:207], v[106:109]
	s_setprio 0
	s_setprio 1
	v_mfma_f32_16x16x32_bf16 v[150:153], v[26:29], v[172:175], v[150:153]
	v_mfma_f32_16x16x32_bf16 v[146:149], v[50:53], v[172:175], v[146:149]
	v_mfma_f32_16x16x32_bf16 v[134:137], v[26:29], v[184:187], v[134:137]
	v_mfma_f32_16x16x32_bf16 v[130:133], v[50:53], v[184:187], v[130:133]
	v_mfma_f32_16x16x32_bf16 v[118:121], v[26:29], v[192:195], v[118:121]
	v_mfma_f32_16x16x32_bf16 v[114:117], v[50:53], v[192:195], v[114:117]
	v_mfma_f32_16x16x32_bf16 v[102:105], v[26:29], v[200:203], v[102:105]
	v_mfma_f32_16x16x32_bf16 v[98:101], v[50:53], v[200:203], v[98:101]
	v_mfma_f32_16x16x32_bf16 v[150:153], v[38:41], v[176:179], v[150:153]
	v_mfma_f32_16x16x32_bf16 v[146:149], v[54:57], v[176:179], v[146:149]
	v_mfma_f32_16x16x32_bf16 v[134:137], v[38:41], v[188:191], v[134:137]
	v_mfma_f32_16x16x32_bf16 v[130:133], v[54:57], v[188:191], v[130:133]
	s_setprio 2
	s_barrier
	v_mfma_f32_16x16x32_bf16 v[118:121], v[38:41], v[196:199], v[118:121]
	v_mfma_f32_16x16x32_bf16 v[114:117], v[54:57], v[196:199], v[114:117]
	v_mfma_f32_16x16x32_bf16 v[102:105], v[38:41], v[204:207], v[102:105]
	v_mfma_f32_16x16x32_bf16 v[98:101], v[54:57], v[204:207], v[98:101]
	s_setprio 0
	s_nop 0
	s_add_i32 s65, s65, s2
	v_lshl_add_u64 v[208:209], s[88:89], 0, v[0:1]
	s_mov_b32 m0, s65
	ds_read_b128 v[172:175], v183 offset:16384
	ds_read_b128 v[176:179], v183 offset:17408
	ds_read_b128 v[184:187], v183 offset:18432
	ds_read_b128 v[188:191], v183 offset:19456
	ds_read_b128 v[192:195], v183 offset:20480
	ds_read_b128 v[196:199], v183 offset:21504
	ds_read_b128 v[200:203], v183 offset:22528
	ds_read_b128 v[204:207], v183 offset:23552
	global_load_lds_dwordx4 v[208:209], off
	s_add_i32 m0, s65, 0x2000
	s_add_u32 s96, s88, 0x4000
	v_lshl_add_u64 v[208:209], s[88:89], 0, v[162:163]
	s_addc_u32 s97, s89, 0
	s_add_i32 s65, s66, s2
	global_load_lds_dwordx4 v[208:209], off
	v_lshl_add_u64 v[208:209], s[96:97], 0, v[0:1]
	s_mov_b32 m0, s65
	s_nop 0
	global_load_lds_dwordx4 v[208:209], off
	v_lshl_add_u64 v[208:209], s[96:97], 0, v[162:163]
	s_add_i32 m0, s65, 0x2000
	s_nop 0
	global_load_lds_dwordx4 v[208:209], off
	v_lshl_add_u64 v[208:209], s[90:91], 0, v[166:167]
	s_mov_b32 m0, s51
	s_nop 0
	global_load_lds_dwordx4 v[208:209], off
	v_lshl_add_u64 v[208:209], s[90:91], 0, v[164:165]
	s_mov_b32 m0, s92
	s_nop 0
	global_load_lds_dwordx4 v[208:209], off
	s_waitcnt vmcnt(8)
	s_waitcnt lgkmcnt(0)
	s_barrier
; #define PG8_STAGE(bufoff, gbase, voff) do { _Pragma("unroll") for (int _i = 0; _i < 2; ++_i) \
;         __builtin_amdgcn_global_load_lds((const unsigned*)((const char*)(gbase) + (voff)[_i]), (PG8_LAS unsigned*)(lds + (bufoff) + ldsw + _i * 8192), 16, 0, 0); } while (0)
; #define PG8_LDA(dst, b, h) do { _Pragma("unroll") for (int m = 0; m < 4; ++m) _Pragma("unroll") for (int k = 0; k < 2; ++k) dst[m][k] = *(const PG8_LAS bf16x8*)(lds + PG8_SA(b, h) + aoff + m * 2048 + k * 1024); } while (0)
; #define PG8_LDB(dst, b, h) do { _Pragma("unroll") for (int n = 0; n < 2; ++n) _Pragma("unroll") for (int k = 0; k < 2; ++k) dst[n][k] = *(const PG8_LAS bf16x8*)(lds + PG8_SB(b, h) + boff + n * 2048 + k * 1024); } while (0)
; #define PG8_MMA(ai, bj, At, Bt) do { __builtin_amdgcn_s_setprio(1); _Pragma("unroll") for (int m = 0; m < 4; ++m) _Pragma("unroll") for (int n = 0; n < 2; ++n) _Pragma("unroll") for (int k = 0; k < 2; ++k) \
;         acc[ai][bj][m][n] = __builtin_amdgcn_mfma_f32_16x16x32_bf16(Bt[n][k], At[m][k], acc[ai][bj][m][n], 0, 0, 0); __builtin_amdgcn_s_setprio(0); } while (0)
; #define PG8_WAIT_V(n) asm volatile("s_waitcnt vmcnt(" #n ")" ::: "memory")
; #define PG8_WAIT_L(n) asm volatile("s_waitcnt lgkmcnt(" #n ")" ::: "memory")
; #define PG8_BAR __builtin_amdgcn_s_barrier()
; #define PG8_SCHED __builtin_amdgcn_sched_barrier(0)
;     ...
;             PG8_LDB(B0, 0, 0); PG8_LDB(B1, 0, 1); PG8_SCHED; PG8_LDA(At, 0, 0); PG8_STAGE(PG8_SA(1, 1), a1 + hstepA, voffA);
;             PG8_WAIT_V(8); PG8_WAIT_L(0); PG8_BAR; PG8_MMA(0, 0, At, B0); PG8_MMA(0, 1, At, B1); PG8_BAR; PG8_SCHED;
;             PG8_LDA(At, 0, 1); PG8_STAGE(PG8_SB(0, 0), b2, voffB); PG8_STAGE(PG8_SB(0, 1), b2 + hstepB, voffB); PG8_STAGE(PG8_SA(0, 0), a2, voffA);
;             PG8_WAIT_V(8); PG8_WAIT_L(0); PG8_BAR; PG8_MMA(1, 0, At, B0); PG8_MMA(1, 1, At, B1); PG8_BAR; PG8_SCHED;
;             PG8_LDB(B0, 1, 0); PG8_LDB(B1, 1, 1); PG8_SCHED; PG8_LDA(At, 1, 0); PG8_STAGE(PG8_SA(0, 1), a2 + hstepA, voffA);
;             PG8_WAIT_V(8); PG8_WAIT_L(0); PG8_BAR; PG8_MMA(0, 0, At, B0); PG8_MMA(0, 1, At, B1); PG8_BAR; PG8_SCHED;
;             PG8_LDA(At, 1, 1); PG8_STAGE(PG8_SB(1, 0), b3, voffB); PG8_STAGE(PG8_SB(1, 1), b3 + hstepB, voffB); PG8_STAGE(PG8_SA(1, 0), a3, voffA);
;             PG8_WAIT_V(8); PG8_WAIT_L(0); PG8_BAR; PG8_MMA(1, 0, At, B0); PG8_MMA(1, 1, At, B1); PG8_BAR; PG8_SCHED;
	s_setprio 1
	s_waitcnt lgkmcnt(0)
	v_mfma_f32_16x16x32_bf16 v[94:97], v[10:13], v[172:175], v[94:97]
	v_mfma_f32_16x16x32_bf16 v[90:93], v[18:21], v[172:175], v[90:93]
	v_mfma_f32_16x16x32_bf16 v[78:81], v[10:13], v[184:187], v[78:81]
	v_mfma_f32_16x16x32_bf16 v[74:77], v[18:21], v[184:187], v[74:77]
	v_mfma_f32_16x16x32_bf16 v[62:65], v[10:13], v[192:195], v[62:65]
	v_mfma_f32_16x16x32_bf16 v[58:61], v[18:21], v[192:195], v[58:61]
	v_mfma_f32_16x16x32_bf16 v[10:13], v[10:13], v[200:203], v[34:37]
	v_mfma_f32_16x16x32_bf16 v[94:97], v[14:17], v[176:179], v[94:97]
	v_mfma_f32_16x16x32_bf16 v[90:93], v[22:25], v[176:179], v[90:93]
	v_mfma_f32_16x16x32_bf16 v[78:81], v[14:17], v[188:191], v[78:81]
	v_mfma_f32_16x16x32_bf16 v[74:77], v[22:25], v[188:191], v[74:77]
	v_mfma_f32_16x16x32_bf16 v[62:65], v[14:17], v[196:199], v[62:65]
	v_mfma_f32_16x16x32_bf16 v[58:61], v[22:25], v[196:199], v[58:61]
	v_mfma_f32_16x16x32_bf16 v[10:13], v[14:17], v[204:207], v[10:13]
	v_mfma_f32_16x16x32_bf16 v[14:17], v[18:21], v[200:203], v[30:33]
	v_mfma_f32_16x16x32_bf16 v[14:17], v[22:25], v[204:207], v[14:17]
	s_setprio 0
	s_setprio 1
	v_mfma_f32_16x16x32_bf16 v[30:33], v[26:29], v[184:187], v[70:73]
	v_mfma_f32_16x16x32_bf16 v[70:73], v[38:41], v[188:191], v[30:33]
	v_mfma_f32_16x16x32_bf16 v[30:33], v[50:53], v[184:187], v[66:69]
	v_mfma_f32_16x16x32_bf16 v[66:69], v[54:57], v[188:191], v[30:33]
	v_mfma_f32_16x16x32_bf16 v[30:33], v[26:29], v[192:195], v[46:49]
	v_mfma_f32_16x16x32_bf16 v[46:49], v[38:41], v[196:199], v[30:33]
	v_mfma_f32_16x16x32_bf16 v[30:33], v[50:53], v[192:195], v[42:45]
	v_mfma_f32_16x16x32_bf16 v[6:9], v[26:29], v[200:203], v[6:9]
	v_mfma_f32_16x16x32_bf16 v[2:5], v[50:53], v[200:203], v[2:5]
	v_mfma_f32_16x16x32_bf16 v[18:21], v[26:29], v[172:175], v[86:89]
	v_mfma_f32_16x16x32_bf16 v[22:25], v[50:53], v[172:175], v[82:85]
	v_mfma_f32_16x16x32_bf16 v[42:45], v[54:57], v[196:199], v[30:33]
	s_setprio 2
	s_barrier
	v_mfma_f32_16x16x32_bf16 v[6:9], v[38:41], v[204:207], v[6:9]
	v_mfma_f32_16x16x32_bf16 v[2:5], v[54:57], v[204:207], v[2:5]
	v_mfma_f32_16x16x32_bf16 v[18:21], v[38:41], v[176:179], v[18:21]
	v_mfma_f32_16x16x32_bf16 v[22:25], v[54:57], v[176:179], v[22:25]
	s_setprio 0
	s_nop 0
	s_add_i32 s65, 0, 0x18000
	v_add_u32_e32 v34, s65, v182
	s_add_i32 s66, 0, 0x1c000
	ds_read_b128 v[26:29], v34
	ds_read_b128 v[30:33], v34 offset:1024
	ds_read_b128 v[38:41], v34 offset:2048
	ds_read_b128 v[50:53], v34 offset:3072
	v_add_u32_e32 v34, s66, v182
	ds_read_b128 v[54:57], v34
	ds_read_b128 v[172:175], v34 offset:1024
	ds_read_b128 v[176:179], v34 offset:2048
	ds_read_b128 v[184:187], v34 offset:3072
	s_add_u32 s90, s90, 0x4000
	s_addc_u32 s91, s91, 0
	s_mov_b32 m0, s14
	v_lshl_add_u64 v[208:209], s[90:91], 0, v[166:167]
	ds_read_b128 v[34:37], v183 offset:32768
	ds_read_b128 v[82:85], v183 offset:33792
	ds_read_b128 v[86:89], v183 offset:34816
	ds_read_b128 v[188:191], v183 offset:35840
	ds_read_b128 v[192:195], v183 offset:36864
	ds_read_b128 v[196:199], v183 offset:37888
	ds_read_b128 v[200:203], v183 offset:38912
	ds_read_b128 v[204:207], v183 offset:39936
	global_load_lds_dwordx4 v[208:209], off
	v_lshl_add_u64 v[208:209], s[90:91], 0, v[164:165]
	s_mov_b32 m0, s15
	s_nop 0
	global_load_lds_dwordx4 v[208:209], off
	s_waitcnt vmcnt(8)
	s_waitcnt lgkmcnt(0)
	s_barrier
	s_setprio 1
	s_waitcnt lgkmcnt(0)
	v_mfma_f32_16x16x32_bf16 v[158:161], v[26:29], v[34:37], v[158:161]
	v_mfma_f32_16x16x32_bf16 v[154:157], v[38:41], v[34:37], v[154:157]
	v_mfma_f32_16x16x32_bf16 v[142:145], v[26:29], v[86:89], v[142:145]
	v_mfma_f32_16x16x32_bf16 v[138:141], v[38:41], v[86:89], v[138:141]
	v_mfma_f32_16x16x32_bf16 v[126:129], v[26:29], v[192:195], v[126:129]
	v_mfma_f32_16x16x32_bf16 v[122:125], v[38:41], v[192:195], v[122:125]
	v_mfma_f32_16x16x32_bf16 v[110:113], v[26:29], v[200:203], v[110:113]
	v_mfma_f32_16x16x32_bf16 v[106:109], v[38:41], v[200:203], v[106:109]
	v_mfma_f32_16x16x32_bf16 v[158:161], v[30:33], v[82:85], v[158:161]
	v_mfma_f32_16x16x32_bf16 v[154:157], v[50:53], v[82:85], v[154:157]
	v_mfma_f32_16x16x32_bf16 v[142:145], v[30:33], v[188:191], v[142:145]
	v_mfma_f32_16x16x32_bf16 v[138:141], v[50:53], v[188:191], v[138:141]
	v_mfma_f32_16x16x32_bf16 v[126:129], v[30:33], v[196:199], v[126:129]
	v_mfma_f32_16x16x32_bf16 v[122:125], v[50:53], v[196:199], v[122:125]
	v_mfma_f32_16x16x32_bf16 v[110:113], v[30:33], v[204:207], v[110:113]
	v_mfma_f32_16x16x32_bf16 v[106:109], v[50:53], v[204:207], v[106:109]
	s_setprio 0
	s_setprio 1
	v_mfma_f32_16x16x32_bf16 v[150:153], v[54:57], v[34:37], v[150:153]
	v_mfma_f32_16x16x32_bf16 v[34:37], v[176:179], v[34:37], v[146:149]
	v_mfma_f32_16x16x32_bf16 v[146:149], v[184:187], v[82:85], v[34:37]
	v_mfma_f32_16x16x32_bf16 v[34:37], v[54:57], v[86:89], v[134:137]
	v_mfma_f32_16x16x32_bf16 v[134:137], v[172:175], v[188:191], v[34:37]
	v_mfma_f32_16x16x32_bf16 v[34:37], v[176:179], v[86:89], v[130:133]
	v_mfma_f32_16x16x32_bf16 v[130:133], v[184:187], v[188:191], v[34:37]
	v_mfma_f32_16x16x32_bf16 v[34:37], v[54:57], v[192:195], v[118:121]
	v_mfma_f32_16x16x32_bf16 v[118:121], v[172:175], v[196:199], v[34:37]
	v_mfma_f32_16x16x32_bf16 v[34:37], v[176:179], v[192:195], v[114:117]
	v_mfma_f32_16x16x32_bf16 v[114:117], v[184:187], v[196:199], v[34:37]
	v_mfma_f32_16x16x32_bf16 v[34:37], v[54:57], v[200:203], v[102:105]
	s_setprio 2
	s_barrier
; #define PG8_STAGE(bufoff, gbase, voff) do { _Pragma("unroll") for (int _i = 0; _i < 2; ++_i) \
;         __builtin_amdgcn_global_load_lds((const unsigned*)((const char*)(gbase) + (voff)[_i]), (PG8_LAS unsigned*)(lds + (bufoff) + ldsw + _i * 8192), 16, 0, 0); } while (0)
; #define PG8_LDA(dst, b, h) do { _Pragma("unroll") for (int m = 0; m < 4; ++m) _Pragma("unroll") for (int k = 0; k < 2; ++k) dst[m][k] = *(const PG8_LAS bf16x8*)(lds + PG8_SA(b, h) + aoff + m * 2048 + k * 1024); } while (0)
; #define PG8_LDB(dst, b, h) do { _Pragma("unroll") for (int n = 0; n < 2; ++n) _Pragma("unroll") for (int k = 0; k < 2; ++k) dst[n][k] = *(const PG8_LAS bf16x8*)(lds + PG8_SB(b, h) + boff + n * 2048 + k * 1024); } while (0)
; #define PG8_WAIT_V(n) asm volatile("s_waitcnt vmcnt(" #n ")" ::: "memory")
; #define PG8_WAIT_L(n) asm volatile("s_waitcnt lgkmcnt(" #n ")" ::: "memory")
;     ...
;         for (int t = 0; t < nt; t += 2) {
;             const bool last = (t == nt - 2);
;             const char* a1 = cA + (ptrdiff_t)(t + 1) * kstepA;
;             const char* a2 = last ? nA : cA + (ptrdiff_t)(t + 2) * kstepA; const char* b2 = last ? nB : cB + (ptrdiff_t)(t + 2) * kstep;
;             const char* a3 = a2 + kstepA; const char* b3 = b2 + kstep;
;             if (last && has_next) S.a_ready(nxt);
;             if constexpr (SP2) {
;             PG8_LDB(B0, 0, 0); PG8_LDB(B1, 0, 1); PG8_SCHED; PG8_LDA(At, 0, 0); PG8_STAGE(PG8_SA(1, 1), a1 + hstepA, voffA);
;             PG8_WAIT_V(8); PG8_WAIT_L(0); PG8_BAR; PG8_MMA(0, 0, At, B0); PG8_MMA(0, 1, At, B1); PG8_BAR; PG8_SCHED;
;             PG8_LDA(At, 0, 1); PG8_STAGE(PG8_SB(0, 0), b2, voffB); PG8_STAGE(PG8_SB(0, 1), b2 + hstepB, voffB); PG8_STAGE(PG8_SA(0, 0), a2, voffA);
;             PG8_WAIT_V(8); PG8_WAIT_L(0); PG8_BAR; PG8_MMA(1, 0, At, B0); PG8_MMA(1, 1, At, B1); PG8_BAR; PG8_SCHED;
;             PG8_LDB(B0, 1, 0); PG8_LDB(B1, 1, 1); PG8_SCHED; PG8_LDA(At, 1, 0); PG8_STAGE(PG8_SA(0, 1), a2 + hstepA, voffA);
;             PG8_WAIT_V(8); PG8_WAIT_L(0); PG8_BAR; PG8_MMA(0, 0, At, B0); PG8_MMA(0, 1, At, B1); PG8_BAR; PG8_SCHED;
;             PG8_LDA(At, 1, 1); PG8_STAGE(PG8_SB(1, 0), b3, voffB); PG8_STAGE(PG8_SB(1, 1), b3 + hstepB, voffB); PG8_STAGE(PG8_SA(1, 0), a3, voffA);
;             PG8_WAIT_V(8); PG8_WAIT_L(0); PG8_BAR; PG8_MMA(1, 0, At, B0); PG8_MMA(1, 1, At, B1); PG8_BAR; PG8_SCHED;
	v_mfma_f32_16x16x32_bf16 v[102:105], v[172:175], v[204:207], v[34:37]
	v_mfma_f32_16x16x32_bf16 v[34:37], v[176:179], v[200:203], v[98:101]
	v_mfma_f32_16x16x32_bf16 v[150:153], v[172:175], v[82:85], v[150:153]
	v_mfma_f32_16x16x32_bf16 v[98:101], v[184:187], v[204:207], v[34:37]
	s_setprio 0
	s_nop 0
	s_add_u32 s90, s88, 0x8000
	s_addc_u32 s91, s89, 0
	s_add_i32 s65, s65, s2
	s_nop 0
	v_lshl_add_u64 v[34:35], s[90:91], 0, v[0:1]
	s_mov_b32 m0, s65
	ds_read_b128 v[82:85], v183 offset:49152
	ds_read_b128 v[188:191], v183 offset:50176
	ds_read_b128 v[192:195], v183 offset:51200
	ds_read_b128 v[196:199], v183 offset:52224
	ds_read_b128 v[200:203], v183 offset:53248
	ds_read_b128 v[204:207], v183 offset:54272
	ds_read_b128 v[208:211], v183 offset:55296
	ds_read_b128 v[216:219], v183 offset:56320
	global_load_lds_dwordx4 v[34:35], off
	s_add_i32 m0, s65, 0x2000
	s_add_u32 s88, s88, 0xc000
	v_lshl_add_u64 v[34:35], s[90:91], 0, v[162:163]
	s_addc_u32 s89, s89, 0
	s_add_i32 s65, s66, s2
	global_load_lds_dwordx4 v[34:35], off
	v_lshl_add_u64 v[34:35], s[88:89], 0, v[0:1]
	s_mov_b32 m0, s65
	s_nop 0
	global_load_lds_dwordx4 v[34:35], off
	v_lshl_add_u64 v[34:35], s[88:89], 0, v[162:163]
	s_add_i32 m0, s65, 0x2000
	s_nop 0
	global_load_lds_dwordx4 v[34:35], off
	v_lshl_add_u64 v[34:35], s[86:87], 0, v[166:167]
	s_mov_b32 m0, s71
	s_nop 0
	global_load_lds_dwordx4 v[34:35], off
	v_lshl_add_u64 v[34:35], s[86:87], 0, v[164:165]
	s_mov_b32 m0, s80
	s_nop 0
	global_load_lds_dwordx4 v[34:35], off
	s_waitcnt vmcnt(8)
	s_waitcnt lgkmcnt(0)
	s_barrier
	s_setprio 1
	s_waitcnt lgkmcnt(0)
	v_mfma_f32_16x16x32_bf16 v[34:37], v[26:29], v[82:85], v[94:97]
	v_mfma_f32_16x16x32_bf16 v[94:97], v[30:33], v[188:191], v[34:37]
	v_mfma_f32_16x16x32_bf16 v[34:37], v[38:41], v[82:85], v[90:93]
	v_mfma_f32_16x16x32_bf16 v[90:93], v[50:53], v[188:191], v[34:37]
	v_mfma_f32_16x16x32_bf16 v[34:37], v[26:29], v[192:195], v[78:81]
	v_mfma_f32_16x16x32_bf16 v[78:81], v[30:33], v[196:199], v[34:37]
	v_mfma_f32_16x16x32_bf16 v[34:37], v[38:41], v[192:195], v[74:77]
	v_mfma_f32_16x16x32_bf16 v[74:77], v[50:53], v[196:199], v[34:37]
	v_mfma_f32_16x16x32_bf16 v[34:37], v[26:29], v[200:203], v[62:65]
	v_mfma_f32_16x16x32_bf16 v[62:65], v[30:33], v[204:207], v[34:37]
	v_mfma_f32_16x16x32_bf16 v[34:37], v[38:41], v[200:203], v[58:61]
	v_mfma_f32_16x16x32_bf16 v[10:13], v[26:29], v[208:211], v[10:13]
	v_mfma_f32_16x16x32_bf16 v[58:61], v[50:53], v[204:207], v[34:37]
	v_mfma_f32_16x16x32_bf16 v[34:37], v[30:33], v[216:219], v[10:13]
	v_mfma_f32_16x16x32_bf16 v[10:13], v[38:41], v[208:211], v[14:17]
	v_mfma_f32_16x16x32_bf16 v[30:33], v[50:53], v[216:219], v[10:13]
	s_setprio 0
	s_setprio 1
	v_mfma_f32_16x16x32_bf16 v[10:13], v[54:57], v[82:85], v[18:21]
	v_mfma_f32_16x16x32_bf16 v[86:89], v[172:175], v[188:191], v[10:13]
	v_mfma_f32_16x16x32_bf16 v[10:13], v[176:179], v[82:85], v[22:25]
	v_mfma_f32_16x16x32_bf16 v[82:85], v[184:187], v[188:191], v[10:13]
	v_mfma_f32_16x16x32_bf16 v[10:13], v[54:57], v[192:195], v[70:73]
	v_mfma_f32_16x16x32_bf16 v[70:73], v[172:175], v[196:199], v[10:13]
	v_mfma_f32_16x16x32_bf16 v[10:13], v[176:179], v[192:195], v[66:69]
	v_mfma_f32_16x16x32_bf16 v[66:69], v[184:187], v[196:199], v[10:13]
	v_mfma_f32_16x16x32_bf16 v[10:13], v[54:57], v[200:203], v[46:49]
	v_mfma_f32_16x16x32_bf16 v[46:49], v[172:175], v[204:207], v[10:13]
	v_mfma_f32_16x16x32_bf16 v[10:13], v[176:179], v[200:203], v[42:45]
	v_mfma_f32_16x16x32_bf16 v[6:9], v[54:57], v[208:211], v[6:9]
	s_setprio 2
	s_barrier
	v_mfma_f32_16x16x32_bf16 v[2:5], v[176:179], v[208:211], v[2:5]
	v_mfma_f32_16x16x32_bf16 v[42:45], v[184:187], v[204:207], v[10:13]
	v_mfma_f32_16x16x32_bf16 v[6:9], v[172:175], v[216:219], v[6:9]
	v_mfma_f32_16x16x32_bf16 v[2:5], v[184:187], v[216:219], v[2:5]
	s_setprio 0
	s_nop 0
	s_add_i32 vcc_lo, vcc_lo, 2
	s_add_u32 s6, s6, 0x10000
	s_addc_u32 s7, s7, 0
	s_add_u32 s56, s56, 0x10000
	s_addc_u32 s57, s57, 0
	s_cmp_gt_u32 vcc_lo, 29
	s_cbranch_scc0 .LBB0_328
	s_and_b64 vcc, exec, s[26:27]
	s_cbranch_vccz .LBB0_331
	s_barrier

; #define PG8_STAGE(bufoff, gbase, voff) do { _Pragma("unroll") for (int _i = 0; _i < 2; ++_i) \
;         __builtin_amdgcn_global_load_lds((const unsigned*)((const char*)(gbase) + (voff)[_i]), (PG8_LAS unsigned*)(lds + (bufoff) + ldsw + _i * 8192), 16, 0, 0); } while (0)
; #define PG8_LDA(dst, b, h) do { _Pragma("unroll") for (int m = 0; m < 4; ++m) _Pragma("unroll") for (int k = 0; k < 2; ++k) dst[m][k] = *(const PG8_LAS bf16x8*)(lds + PG8_SA(b, h) + aoff + m * 2048 + k * 1024); } while (0)
; #define PG8_LDB(dst, b, h) do { _Pragma("unroll") for (int n = 0; n < 2; ++n) _Pragma("unroll") for (int k = 0; k < 2; ++k) dst[n][k] = *(const PG8_LAS bf16x8*)(lds + PG8_SB(b, h) + boff + n * 2048 + k * 1024); } while (0)
; #define PG8_WAIT_V(n) asm volatile("s_waitcnt vmcnt(" #n ")" ::: "memory")
; #define PG8_WAIT_L(n) asm volatile("s_waitcnt lgkmcnt(" #n ")" ::: "memory")
;     ...
;         for (int t = 0; t < nt; t += 2) {
;             const bool last = (t == nt - 2);
;             const char* a1 = cA + (ptrdiff_t)(t + 1) * kstepA;
;             const char* a2 = last ? nA : cA + (ptrdiff_t)(t + 2) * kstepA; const char* b2 = last ? nB : cB + (ptrdiff_t)(t + 2) * kstep;
;             const char* a3 = a2 + kstepA; const char* b3 = b2 + kstep;
;             if (last && has_next) S.a_ready(nxt);
;             if constexpr (SP2) {
;             PG8_LDB(B0, 0, 0); PG8_LDB(B1, 0, 1); PG8_SCHED; PG8_LDA(At, 0, 0); PG8_STAGE(PG8_SA(1, 1), a1 + hstepA, voffA);
;             PG8_WAIT_V(8); PG8_WAIT_L(0); PG8_BAR; PG8_MMA(0, 0, At, B0); PG8_MMA(0, 1, At, B1); PG8_BAR; PG8_SCHED;
;             PG8_LDA(At, 0, 1); PG8_STAGE(PG8_SB(0, 0), b2, voffB); PG8_STAGE(PG8_SB(0, 1), b2 + hstepB, voffB); PG8_STAGE(PG8_SA(0, 0), a2, voffA);
;             PG8_WAIT_V(8); PG8_WAIT_L(0); PG8_BAR; PG8_MMA(1, 0, At, B0); PG8_MMA(1, 1, At, B1); PG8_BAR; PG8_SCHED;
;             PG8_LDB(B0, 1, 0); PG8_LDB(B1, 1, 1); PG8_SCHED; PG8_LDA(At, 1, 0); PG8_STAGE(PG8_SA(0, 1), a2 + hstepA, voffA);
;             PG8_WAIT_V(8); PG8_WAIT_L(0); PG8_BAR; PG8_MMA(0, 0, At, B0); PG8_MMA(0, 1, At, B1); PG8_BAR; PG8_SCHED;
;             PG8_LDA(At, 1, 1); PG8_STAGE(PG8_SB(1, 0), b3, voffB); PG8_STAGE(PG8_SB(1, 1), b3 + hstepB, voffB); PG8_STAGE(PG8_SA(1, 0), a3, voffA);
;             PG8_WAIT_V(8); PG8_WAIT_L(0); PG8_BAR; PG8_MMA(1, 0, At, B0); PG8_MMA(1, 1, At, B1); PG8_BAR; PG8_SCHED;
.LBB0_1128:
	s_add_u32 s36, s34, 0x4000
	s_addc_u32 s37, s35, 0
	s_cmp_eq_u32 s57, 28
	s_cselect_b32 s86, s29, s36
	s_cselect_b32 s87, s23, s37
	s_cselect_b32 s46, s31, s44
	s_cselect_b32 s47, s21, s56
	s_add_u32 s36, s86, 0x8000
	s_addc_u32 s37, s87, 0
	s_add_i32 s65, 0, 0x10000
	v_add_u32_e32 v0, s65, v242
	s_add_i32 s66, 0, 0x14000
	s_waitcnt lgkmcnt(0)
	ds_read_b128 v[130:133], v0
	ds_read_b128 v[134:137], v0 offset:1024
	ds_read_b128 v[138:141], v0 offset:2048
	ds_read_b128 v[142:145], v0 offset:3072
	v_add_u32_e32 v0, s66, v242
	ds_read_b128 v[146:149], v0
	ds_read_b128 v[150:153], v0 offset:1024
	ds_read_b128 v[154:157], v0 offset:2048
	ds_read_b128 v[158:161], v0 offset:3072
	v_lshl_add_u64 v[206:207], s[34:35], 0, v[194:195]
	s_add_i32 m0, s51, 0xc000
	ds_read_b128 v[162:165], v243
	ds_read_b128 v[166:169], v243 offset:1024
	ds_read_b128 v[170:173], v243 offset:2048
	ds_read_b128 v[174:177], v243 offset:3072
	ds_read_b128 v[178:181], v243 offset:4096
	ds_read_b128 v[182:185], v243 offset:5120
	ds_read_b128 v[198:201], v243 offset:6144
	ds_read_b128 v[202:205], v243 offset:7168
	global_load_lds_dwordx4 v[206:207], off
	v_lshl_add_u64 v[206:207], s[34:35], 0, v[196:197]
	s_add_i32 m0, s51, 0xe000
	s_nop 0
	global_load_lds_dwordx4 v[206:207], off
	s_waitcnt vmcnt(8)
	s_waitcnt lgkmcnt(0)
	s_barrier
	s_setprio 1
	s_waitcnt lgkmcnt(0)
	v_mfma_f32_16x16x32_bf16 v[126:129], v[130:133], v[162:165], v[126:129]
	v_mfma_f32_16x16x32_bf16 v[122:125], v[138:141], v[162:165], v[122:125]
	v_mfma_f32_16x16x32_bf16 v[110:113], v[130:133], v[170:173], v[110:113]
	v_mfma_f32_16x16x32_bf16 v[106:109], v[138:141], v[170:173], v[106:109]
	v_mfma_f32_16x16x32_bf16 v[94:97], v[130:133], v[178:181], v[94:97]
	v_mfma_f32_16x16x32_bf16 v[90:93], v[138:141], v[178:181], v[90:93]
	v_mfma_f32_16x16x32_bf16 v[78:81], v[130:133], v[198:201], v[78:81]
	v_mfma_f32_16x16x32_bf16 v[74:77], v[138:141], v[198:201], v[74:77]
	v_mfma_f32_16x16x32_bf16 v[126:129], v[134:137], v[166:169], v[126:129]
	v_mfma_f32_16x16x32_bf16 v[122:125], v[142:145], v[166:169], v[122:125]
	v_mfma_f32_16x16x32_bf16 v[110:113], v[134:137], v[174:177], v[110:113]
	v_mfma_f32_16x16x32_bf16 v[106:109], v[142:145], v[174:177], v[106:109]
	v_mfma_f32_16x16x32_bf16 v[94:97], v[134:137], v[182:185], v[94:97]
	v_mfma_f32_16x16x32_bf16 v[90:93], v[142:145], v[182:185], v[90:93]
	v_mfma_f32_16x16x32_bf16 v[78:81], v[134:137], v[202:205], v[78:81]
	v_mfma_f32_16x16x32_bf16 v[74:77], v[142:145], v[202:205], v[74:77]
	s_setprio 0
	s_setprio 1
	v_mfma_f32_16x16x32_bf16 v[118:121], v[146:149], v[162:165], v[118:121]
	v_mfma_f32_16x16x32_bf16 v[114:117], v[154:157], v[162:165], v[114:117]
	v_mfma_f32_16x16x32_bf16 v[102:105], v[146:149], v[170:173], v[102:105]
	v_mfma_f32_16x16x32_bf16 v[98:101], v[154:157], v[170:173], v[98:101]
	v_mfma_f32_16x16x32_bf16 v[86:89], v[146:149], v[178:181], v[86:89]
	v_mfma_f32_16x16x32_bf16 v[82:85], v[154:157], v[178:181], v[82:85]
	v_mfma_f32_16x16x32_bf16 v[70:73], v[146:149], v[198:201], v[70:73]
	v_mfma_f32_16x16x32_bf16 v[66:69], v[154:157], v[198:201], v[66:69]
	v_mfma_f32_16x16x32_bf16 v[118:121], v[150:153], v[166:169], v[118:121]
	v_mfma_f32_16x16x32_bf16 v[114:117], v[158:161], v[166:169], v[114:117]
	v_mfma_f32_16x16x32_bf16 v[102:105], v[150:153], v[174:177], v[102:105]
	v_mfma_f32_16x16x32_bf16 v[98:101], v[158:161], v[174:177], v[98:101]
	s_setprio 2
	s_barrier
	v_mfma_f32_16x16x32_bf16 v[86:89], v[150:153], v[182:185], v[86:89]
	v_mfma_f32_16x16x32_bf16 v[82:85], v[158:161], v[182:185], v[82:85]
	v_mfma_f32_16x16x32_bf16 v[70:73], v[150:153], v[202:205], v[70:73]
	v_mfma_f32_16x16x32_bf16 v[66:69], v[158:161], v[202:205], v[66:69]
	s_setprio 0
	s_nop 0
	s_add_i32 s65, s65, s49
	v_lshl_add_u64 v[206:207], s[46:47], 0, v[188:189]
	s_mov_b32 m0, s65
	ds_read_b128 v[162:165], v243 offset:16384
	ds_read_b128 v[166:169], v243 offset:17408
	ds_read_b128 v[170:173], v243 offset:18432
	ds_read_b128 v[174:177], v243 offset:19456
	ds_read_b128 v[178:181], v243 offset:20480
	ds_read_b128 v[182:185], v243 offset:21504
	ds_read_b128 v[198:201], v243 offset:22528
	ds_read_b128 v[202:205], v243 offset:23552
	global_load_lds_dwordx4 v[206:207], off
	s_add_i32 m0, s65, 0x2000
	s_add_u32 s90, s46, 0x4000
	v_lshl_add_u64 v[206:207], s[46:47], 0, v[192:193]
	s_addc_u32 s91, s47, 0
	s_add_i32 s65, s66, s49
	global_load_lds_dwordx4 v[206:207], off
	v_lshl_add_u64 v[206:207], s[90:91], 0, v[188:189]
	s_mov_b32 m0, s65
	s_nop 0
	global_load_lds_dwordx4 v[206:207], off
	v_lshl_add_u64 v[206:207], s[90:91], 0, v[192:193]
	s_add_i32 m0, s65, 0x2000
	s_nop 0
	global_load_lds_dwordx4 v[206:207], off
	v_lshl_add_u64 v[206:207], s[86:87], 0, v[186:187]
	s_mov_b32 m0, s51
	s_nop 0
	global_load_lds_dwordx4 v[206:207], off
	v_lshl_add_u64 v[206:207], s[86:87], 0, v[190:191]
	s_mov_b32 m0, s54
	s_nop 0
	global_load_lds_dwordx4 v[206:207], off
	s_waitcnt vmcnt(8)
	s_waitcnt lgkmcnt(0)
	s_barrier
; #define PG8_STAGE(bufoff, gbase, voff) do { _Pragma("unroll") for (int _i = 0; _i < 2; ++_i) \
;         __builtin_amdgcn_global_load_lds((const unsigned*)((const char*)(gbase) + (voff)[_i]), (PG8_LAS unsigned*)(lds + (bufoff) + ldsw + _i * 8192), 16, 0, 0); } while (0)
; #define PG8_LDA(dst, b, h) do { _Pragma("unroll") for (int m = 0; m < 4; ++m) _Pragma("unroll") for (int k = 0; k < 2; ++k) dst[m][k] = *(const PG8_LAS bf16x8*)(lds + PG8_SA(b, h) + aoff + m * 2048 + k * 1024); } while (0)
; #define PG8_LDB(dst, b, h) do { _Pragma("unroll") for (int n = 0; n < 2; ++n) _Pragma("unroll") for (int k = 0; k < 2; ++k) dst[n][k] = *(const PG8_LAS bf16x8*)(lds + PG8_SB(b, h) + boff + n * 2048 + k * 1024); } while (0)
; #define PG8_MMA(ai, bj, At, Bt) do { __builtin_amdgcn_s_setprio(1); _Pragma("unroll") for (int m = 0; m < 4; ++m) _Pragma("unroll") for (int n = 0; n < 2; ++n) _Pragma("unroll") for (int k = 0; k < 2; ++k) \
;         acc[ai][bj][m][n] = __builtin_amdgcn_mfma_f32_16x16x32_bf16(Bt[n][k], At[m][k], acc[ai][bj][m][n], 0, 0, 0); __builtin_amdgcn_s_setprio(0); } while (0)
; #define PG8_WAIT_V(n) asm volatile("s_waitcnt vmcnt(" #n ")" ::: "memory")
; #define PG8_WAIT_L(n) asm volatile("s_waitcnt lgkmcnt(" #n ")" ::: "memory")
; #define PG8_BAR __builtin_amdgcn_s_barrier()
; #define PG8_SCHED __builtin_amdgcn_sched_barrier(0)
;     ...
;             PG8_LDB(B0, 0, 0); PG8_LDB(B1, 0, 1); PG8_SCHED; PG8_LDA(At, 0, 0); PG8_STAGE(PG8_SA(1, 1), a1 + hstepA, voffA);
;             PG8_WAIT_V(8); PG8_WAIT_L(0); PG8_BAR; PG8_MMA(0, 0, At, B0); PG8_MMA(0, 1, At, B1); PG8_BAR; PG8_SCHED;
;             PG8_LDA(At, 0, 1); PG8_STAGE(PG8_SB(0, 0), b2, voffB); PG8_STAGE(PG8_SB(0, 1), b2 + hstepB, voffB); PG8_STAGE(PG8_SA(0, 0), a2, voffA);
;             PG8_WAIT_V(8); PG8_WAIT_L(0); PG8_BAR; PG8_MMA(1, 0, At, B0); PG8_MMA(1, 1, At, B1); PG8_BAR; PG8_SCHED;
;             PG8_LDB(B0, 1, 0); PG8_LDB(B1, 1, 1); PG8_SCHED; PG8_LDA(At, 1, 0); PG8_STAGE(PG8_SA(0, 1), a2 + hstepA, voffA);
;             PG8_WAIT_V(8); PG8_WAIT_L(0); PG8_BAR; PG8_MMA(0, 0, At, B0); PG8_MMA(0, 1, At, B1); PG8_BAR; PG8_SCHED;
;             PG8_LDA(At, 1, 1); PG8_STAGE(PG8_SB(1, 0), b3, voffB); PG8_STAGE(PG8_SB(1, 1), b3 + hstepB, voffB); PG8_STAGE(PG8_SA(1, 0), a3, voffA);
;             PG8_WAIT_V(8); PG8_WAIT_L(0); PG8_BAR; PG8_MMA(1, 0, At, B0); PG8_MMA(1, 1, At, B1); PG8_BAR; PG8_SCHED;
	s_setprio 1
	s_waitcnt lgkmcnt(0)
	v_mfma_f32_16x16x32_bf16 v[62:65], v[130:133], v[162:165], v[62:65]
	v_mfma_f32_16x16x32_bf16 v[58:61], v[138:141], v[162:165], v[58:61]
	v_mfma_f32_16x16x32_bf16 v[46:49], v[130:133], v[170:173], v[46:49]
	v_mfma_f32_16x16x32_bf16 v[42:45], v[138:141], v[170:173], v[42:45]
	v_mfma_f32_16x16x32_bf16 v[30:33], v[130:133], v[178:181], v[30:33]
	v_mfma_f32_16x16x32_bf16 v[26:29], v[138:141], v[178:181], v[26:29]
	v_mfma_f32_16x16x32_bf16 v[14:17], v[130:133], v[198:201], v[14:17]
	v_mfma_f32_16x16x32_bf16 v[10:13], v[138:141], v[198:201], v[10:13]
	v_mfma_f32_16x16x32_bf16 v[62:65], v[134:137], v[166:169], v[62:65]
	v_mfma_f32_16x16x32_bf16 v[58:61], v[142:145], v[166:169], v[58:61]
	v_mfma_f32_16x16x32_bf16 v[46:49], v[134:137], v[174:177], v[46:49]
	v_mfma_f32_16x16x32_bf16 v[42:45], v[142:145], v[174:177], v[42:45]
	v_mfma_f32_16x16x32_bf16 v[30:33], v[134:137], v[182:185], v[30:33]
	v_mfma_f32_16x16x32_bf16 v[26:29], v[142:145], v[182:185], v[26:29]
	v_mfma_f32_16x16x32_bf16 v[14:17], v[134:137], v[202:205], v[14:17]
	v_mfma_f32_16x16x32_bf16 v[10:13], v[142:145], v[202:205], v[10:13]
	s_setprio 0
	s_setprio 1
	v_mfma_f32_16x16x32_bf16 v[54:57], v[146:149], v[162:165], v[54:57]
	v_mfma_f32_16x16x32_bf16 v[50:53], v[154:157], v[162:165], v[50:53]
	v_mfma_f32_16x16x32_bf16 v[38:41], v[146:149], v[170:173], v[38:41]
	v_mfma_f32_16x16x32_bf16 v[34:37], v[154:157], v[170:173], v[34:37]
	v_mfma_f32_16x16x32_bf16 v[22:25], v[146:149], v[178:181], v[22:25]
	v_mfma_f32_16x16x32_bf16 v[18:21], v[154:157], v[178:181], v[18:21]
	v_mfma_f32_16x16x32_bf16 v[6:9], v[146:149], v[198:201], v[6:9]
	v_mfma_f32_16x16x32_bf16 v[2:5], v[154:157], v[198:201], v[2:5]
	v_mfma_f32_16x16x32_bf16 v[54:57], v[150:153], v[166:169], v[54:57]
	v_mfma_f32_16x16x32_bf16 v[50:53], v[158:161], v[166:169], v[50:53]
	v_mfma_f32_16x16x32_bf16 v[38:41], v[150:153], v[174:177], v[38:41]
	v_mfma_f32_16x16x32_bf16 v[34:37], v[158:161], v[174:177], v[34:37]
	s_setprio 2
	s_barrier
	v_mfma_f32_16x16x32_bf16 v[22:25], v[150:153], v[182:185], v[22:25]
	v_mfma_f32_16x16x32_bf16 v[18:21], v[158:161], v[182:185], v[18:21]
	v_mfma_f32_16x16x32_bf16 v[6:9], v[150:153], v[202:205], v[6:9]
	v_mfma_f32_16x16x32_bf16 v[2:5], v[158:161], v[202:205], v[2:5]
	s_setprio 0
	s_nop 0
	s_add_i32 s65, 0, 0x18000
	v_add_u32_e32 v0, s65, v242
	s_add_i32 s66, 0, 0x1c000
	ds_read_b128 v[130:133], v0
	ds_read_b128 v[134:137], v0 offset:1024
	ds_read_b128 v[138:141], v0 offset:2048
	ds_read_b128 v[142:145], v0 offset:3072
	v_add_u32_e32 v0, s66, v242
	ds_read_b128 v[146:149], v0
	ds_read_b128 v[150:153], v0 offset:1024
	ds_read_b128 v[154:157], v0 offset:2048
	ds_read_b128 v[158:161], v0 offset:3072
	s_add_u32 s86, s86, 0x4000
	s_addc_u32 s87, s87, 0
	s_mov_b32 m0, s55
	v_lshl_add_u64 v[206:207], s[86:87], 0, v[186:187]
	ds_read_b128 v[162:165], v243 offset:32768
	ds_read_b128 v[166:169], v243 offset:33792
	ds_read_b128 v[170:173], v243 offset:34816
	ds_read_b128 v[174:177], v243 offset:35840
	ds_read_b128 v[178:181], v243 offset:36864
	ds_read_b128 v[182:185], v243 offset:37888
	ds_read_b128 v[198:201], v243 offset:38912
	ds_read_b128 v[202:205], v243 offset:39936
	global_load_lds_dwordx4 v[206:207], off
	v_lshl_add_u64 v[206:207], s[86:87], 0, v[190:191]
	s_mov_b32 m0, s61
	s_nop 0
	global_load_lds_dwordx4 v[206:207], off
	s_waitcnt vmcnt(8)
	s_waitcnt lgkmcnt(0)
	s_barrier
	s_setprio 1
	s_waitcnt lgkmcnt(0)
	v_mfma_f32_16x16x32_bf16 v[126:129], v[130:133], v[162:165], v[126:129]
	v_mfma_f32_16x16x32_bf16 v[122:125], v[138:141], v[162:165], v[122:125]
	v_mfma_f32_16x16x32_bf16 v[110:113], v[130:133], v[170:173], v[110:113]
	v_mfma_f32_16x16x32_bf16 v[106:109], v[138:141], v[170:173], v[106:109]
	v_mfma_f32_16x16x32_bf16 v[94:97], v[130:133], v[178:181], v[94:97]
	v_mfma_f32_16x16x32_bf16 v[90:93], v[138:141], v[178:181], v[90:93]
	v_mfma_f32_16x16x32_bf16 v[78:81], v[130:133], v[198:201], v[78:81]
	v_mfma_f32_16x16x32_bf16 v[74:77], v[138:141], v[198:201], v[74:77]
	v_mfma_f32_16x16x32_bf16 v[126:129], v[134:137], v[166:169], v[126:129]
	v_mfma_f32_16x16x32_bf16 v[122:125], v[142:145], v[166:169], v[122:125]
	v_mfma_f32_16x16x32_bf16 v[110:113], v[134:137], v[174:177], v[110:113]
	v_mfma_f32_16x16x32_bf16 v[106:109], v[142:145], v[174:177], v[106:109]
	v_mfma_f32_16x16x32_bf16 v[94:97], v[134:137], v[182:185], v[94:97]
	v_mfma_f32_16x16x32_bf16 v[90:93], v[142:145], v[182:185], v[90:93]
	v_mfma_f32_16x16x32_bf16 v[78:81], v[134:137], v[202:205], v[78:81]
	v_mfma_f32_16x16x32_bf16 v[74:77], v[142:145], v[202:205], v[74:77]
	s_setprio 0
	s_setprio 1
	v_mfma_f32_16x16x32_bf16 v[118:121], v[146:149], v[162:165], v[118:121]
	v_mfma_f32_16x16x32_bf16 v[114:117], v[154:157], v[162:165], v[114:117]
	v_mfma_f32_16x16x32_bf16 v[102:105], v[146:149], v[170:173], v[102:105]
	v_mfma_f32_16x16x32_bf16 v[98:101], v[154:157], v[170:173], v[98:101]
	v_mfma_f32_16x16x32_bf16 v[86:89], v[146:149], v[178:181], v[86:89]
	v_mfma_f32_16x16x32_bf16 v[82:85], v[154:157], v[178:181], v[82:85]
	v_mfma_f32_16x16x32_bf16 v[70:73], v[146:149], v[198:201], v[70:73]
	v_mfma_f32_16x16x32_bf16 v[66:69], v[154:157], v[198:201], v[66:69]
	v_mfma_f32_16x16x32_bf16 v[118:121], v[150:153], v[166:169], v[118:121]
	v_mfma_f32_16x16x32_bf16 v[114:117], v[158:161], v[166:169], v[114:117]
	v_mfma_f32_16x16x32_bf16 v[102:105], v[150:153], v[174:177], v[102:105]
	v_mfma_f32_16x16x32_bf16 v[98:101], v[158:161], v[174:177], v[98:101]
	s_setprio 2
	s_barrier
; #define PG8_STAGE(bufoff, gbase, voff) do { _Pragma("unroll") for (int _i = 0; _i < 2; ++_i) \
;         __builtin_amdgcn_global_load_lds((const unsigned*)((const char*)(gbase) + (voff)[_i]), (PG8_LAS unsigned*)(lds + (bufoff) + ldsw + _i * 8192), 16, 0, 0); } while (0)
; #define PG8_LDA(dst, b, h) do { _Pragma("unroll") for (int m = 0; m < 4; ++m) _Pragma("unroll") for (int k = 0; k < 2; ++k) dst[m][k] = *(const PG8_LAS bf16x8*)(lds + PG8_SA(b, h) + aoff + m * 2048 + k * 1024); } while (0)
; #define PG8_LDB(dst, b, h) do { _Pragma("unroll") for (int n = 0; n < 2; ++n) _Pragma("unroll") for (int k = 0; k < 2; ++k) dst[n][k] = *(const PG8_LAS bf16x8*)(lds + PG8_SB(b, h) + boff + n * 2048 + k * 1024); } while (0)
; #define PG8_WAIT_V(n) asm volatile("s_waitcnt vmcnt(" #n ")" ::: "memory")
; #define PG8_WAIT_L(n) asm volatile("s_waitcnt lgkmcnt(" #n ")" ::: "memory")
;     ...
;         for (int t = 0; t < nt; t += 2) {
;             const bool last = (t == nt - 2);
;             const char* a1 = cA + (ptrdiff_t)(t + 1) * kstepA;
;             const char* a2 = last ? nA : cA + (ptrdiff_t)(t + 2) * kstepA; const char* b2 = last ? nB : cB + (ptrdiff_t)(t + 2) * kstep;
;             const char* a3 = a2 + kstepA; const char* b3 = b2 + kstep;
;             if (last && has_next) S.a_ready(nxt);
;             if constexpr (SP2) {
;             PG8_LDB(B0, 0, 0); PG8_LDB(B1, 0, 1); PG8_SCHED; PG8_LDA(At, 0, 0); PG8_STAGE(PG8_SA(1, 1), a1 + hstepA, voffA);
;             PG8_WAIT_V(8); PG8_WAIT_L(0); PG8_BAR; PG8_MMA(0, 0, At, B0); PG8_MMA(0, 1, At, B1); PG8_BAR; PG8_SCHED;
;             PG8_LDA(At, 0, 1); PG8_STAGE(PG8_SB(0, 0), b2, voffB); PG8_STAGE(PG8_SB(0, 1), b2 + hstepB, voffB); PG8_STAGE(PG8_SA(0, 0), a2, voffA);
;             PG8_WAIT_V(8); PG8_WAIT_L(0); PG8_BAR; PG8_MMA(1, 0, At, B0); PG8_MMA(1, 1, At, B1); PG8_BAR; PG8_SCHED;
;             PG8_LDB(B0, 1, 0); PG8_LDB(B1, 1, 1); PG8_SCHED; PG8_LDA(At, 1, 0); PG8_STAGE(PG8_SA(0, 1), a2 + hstepA, voffA);
;             PG8_WAIT_V(8); PG8_WAIT_L(0); PG8_BAR; PG8_MMA(0, 0, At, B0); PG8_MMA(0, 1, At, B1); PG8_BAR; PG8_SCHED;
;             PG8_LDA(At, 1, 1); PG8_STAGE(PG8_SB(1, 0), b3, voffB); PG8_STAGE(PG8_SB(1, 1), b3 + hstepB, voffB); PG8_STAGE(PG8_SA(1, 0), a3, voffA);
;             PG8_WAIT_V(8); PG8_WAIT_L(0); PG8_BAR; PG8_MMA(1, 0, At, B0); PG8_MMA(1, 1, At, B1); PG8_BAR; PG8_SCHED;
	v_mfma_f32_16x16x32_bf16 v[86:89], v[150:153], v[182:185], v[86:89]
	v_mfma_f32_16x16x32_bf16 v[82:85], v[158:161], v[182:185], v[82:85]
	v_mfma_f32_16x16x32_bf16 v[70:73], v[150:153], v[202:205], v[70:73]
	v_mfma_f32_16x16x32_bf16 v[66:69], v[158:161], v[202:205], v[66:69]
	s_setprio 0
	s_nop 0
	s_add_u32 s86, s46, 0x8000
	s_addc_u32 s87, s47, 0
	s_add_i32 s65, s65, s49
	v_lshl_add_u64 v[206:207], s[86:87], 0, v[188:189]
	s_mov_b32 m0, s65
	ds_read_b128 v[162:165], v243 offset:49152
	ds_read_b128 v[166:169], v243 offset:50176
	ds_read_b128 v[170:173], v243 offset:51200
	ds_read_b128 v[174:177], v243 offset:52224
	ds_read_b128 v[178:181], v243 offset:53248
	ds_read_b128 v[182:185], v243 offset:54272
	ds_read_b128 v[198:201], v243 offset:55296
	ds_read_b128 v[202:205], v243 offset:56320
	global_load_lds_dwordx4 v[206:207], off
	s_add_i32 m0, s65, 0x2000
	s_add_u32 s46, s46, 0xc000
	v_lshl_add_u64 v[206:207], s[86:87], 0, v[192:193]
	s_addc_u32 s47, s47, 0
	s_add_i32 s65, s66, s49
	global_load_lds_dwordx4 v[206:207], off
	v_lshl_add_u64 v[206:207], s[46:47], 0, v[188:189]
	s_mov_b32 m0, s65
	s_nop 0
	global_load_lds_dwordx4 v[206:207], off
	v_lshl_add_u64 v[206:207], s[46:47], 0, v[192:193]
	s_add_i32 m0, s65, 0x2000
	s_nop 0
	global_load_lds_dwordx4 v[206:207], off
	v_lshl_add_u64 v[206:207], s[36:37], 0, v[186:187]
	s_mov_b32 m0, s83
	s_nop 0
	global_load_lds_dwordx4 v[206:207], off
	v_lshl_add_u64 v[206:207], s[36:37], 0, v[190:191]
	s_mov_b32 m0, s85
	s_nop 0
	global_load_lds_dwordx4 v[206:207], off
	s_waitcnt vmcnt(8)
	s_waitcnt lgkmcnt(0)
	s_barrier
	s_setprio 1
	s_waitcnt lgkmcnt(0)
	v_mfma_f32_16x16x32_bf16 v[62:65], v[130:133], v[162:165], v[62:65]
	v_mfma_f32_16x16x32_bf16 v[58:61], v[138:141], v[162:165], v[58:61]
	v_mfma_f32_16x16x32_bf16 v[46:49], v[130:133], v[170:173], v[46:49]
	v_mfma_f32_16x16x32_bf16 v[42:45], v[138:141], v[170:173], v[42:45]
	v_mfma_f32_16x16x32_bf16 v[30:33], v[130:133], v[178:181], v[30:33]
	v_mfma_f32_16x16x32_bf16 v[26:29], v[138:141], v[178:181], v[26:29]
	v_mfma_f32_16x16x32_bf16 v[14:17], v[130:133], v[198:201], v[14:17]
	v_mfma_f32_16x16x32_bf16 v[10:13], v[138:141], v[198:201], v[10:13]
	v_mfma_f32_16x16x32_bf16 v[62:65], v[134:137], v[166:169], v[62:65]
	v_mfma_f32_16x16x32_bf16 v[58:61], v[142:145], v[166:169], v[58:61]
	v_mfma_f32_16x16x32_bf16 v[46:49], v[134:137], v[174:177], v[46:49]
	v_mfma_f32_16x16x32_bf16 v[42:45], v[142:145], v[174:177], v[42:45]
	v_mfma_f32_16x16x32_bf16 v[30:33], v[134:137], v[182:185], v[30:33]
	v_mfma_f32_16x16x32_bf16 v[26:29], v[142:145], v[182:185], v[26:29]
	v_mfma_f32_16x16x32_bf16 v[14:17], v[134:137], v[202:205], v[14:17]
	v_mfma_f32_16x16x32_bf16 v[10:13], v[142:145], v[202:205], v[10:13]
	s_setprio 0
	s_setprio 1
	v_mfma_f32_16x16x32_bf16 v[54:57], v[146:149], v[162:165], v[54:57]
	v_mfma_f32_16x16x32_bf16 v[50:53], v[154:157], v[162:165], v[50:53]
	v_mfma_f32_16x16x32_bf16 v[38:41], v[146:149], v[170:173], v[38:41]
	v_mfma_f32_16x16x32_bf16 v[34:37], v[154:157], v[170:173], v[34:37]
	v_mfma_f32_16x16x32_bf16 v[22:25], v[146:149], v[178:181], v[22:25]
	v_mfma_f32_16x16x32_bf16 v[18:21], v[154:157], v[178:181], v[18:21]
	v_mfma_f32_16x16x32_bf16 v[6:9], v[146:149], v[198:201], v[6:9]
	v_mfma_f32_16x16x32_bf16 v[2:5], v[154:157], v[198:201], v[2:5]
	v_mfma_f32_16x16x32_bf16 v[54:57], v[150:153], v[166:169], v[54:57]
	v_mfma_f32_16x16x32_bf16 v[50:53], v[158:161], v[166:169], v[50:53]
	v_mfma_f32_16x16x32_bf16 v[38:41], v[150:153], v[174:177], v[38:41]
	v_mfma_f32_16x16x32_bf16 v[34:37], v[158:161], v[174:177], v[34:37]
	s_setprio 2
	s_barrier
	v_mfma_f32_16x16x32_bf16 v[22:25], v[150:153], v[182:185], v[22:25]
	v_mfma_f32_16x16x32_bf16 v[18:21], v[158:161], v[182:185], v[18:21]
	v_mfma_f32_16x16x32_bf16 v[6:9], v[150:153], v[202:205], v[6:9]
	v_mfma_f32_16x16x32_bf16 v[2:5], v[158:161], v[202:205], v[2:5]
	s_setprio 0
	s_nop 0
	s_add_i32 s57, s57, 2
	s_add_u32 s34, s34, 0x10000
	s_addc_u32 s35, s35, 0
	s_add_u32 s44, s44, 0x10000
	s_addc_u32 s56, s56, 0
	s_cmp_gt_u32 s57, 29
	s_cbranch_scc0 .LBB0_1128
	s_and_b64 vcc, exec, s[92:93]
	s_cbranch_vccz .LBB0_1131
	s_barrier

; #define PG8_STAGE(bufoff, gbase, voff) do { _Pragma("unroll") for (int _i = 0; _i < 2; ++_i) \
;         __builtin_amdgcn_global_load_lds((const unsigned*)((const char*)(gbase) + (voff)[_i]), (PG8_LAS unsigned*)(lds + (bufoff) + ldsw + _i * 8192), 16, 0, 0); } while (0)
; #define PG8_LDA(dst, b, h) do { _Pragma("unroll") for (int m = 0; m < 4; ++m) _Pragma("unroll") for (int k = 0; k < 2; ++k) dst[m][k] = *(const PG8_LAS bf16x8*)(lds + PG8_SA(b, h) + aoff + m * 2048 + k * 1024); } while (0)
; #define PG8_LDB(dst, b, h) do { _Pragma("unroll") for (int n = 0; n < 2; ++n) _Pragma("unroll") for (int k = 0; k < 2; ++k) dst[n][k] = *(const PG8_LAS bf16x8*)(lds + PG8_SB(b, h) + boff + n * 2048 + k * 1024); } while (0)
; #define PG8_WAIT_V(n) asm volatile("s_waitcnt vmcnt(" #n ")" ::: "memory")
; #define PG8_WAIT_L(n) asm volatile("s_waitcnt lgkmcnt(" #n ")" ::: "memory")
;     ...
;         for (int t = 0; t < nt; t += 2) {
;             const bool last = (t == nt - 2);
;             const char* a1 = cA + (ptrdiff_t)(t + 1) * kstepA;
;             const char* a2 = last ? nA : cA + (ptrdiff_t)(t + 2) * kstepA; const char* b2 = last ? nB : cB + (ptrdiff_t)(t + 2) * kstep;
;             const char* a3 = a2 + kstepA; const char* b3 = b2 + kstep;
;             if (last && has_next) S.a_ready(nxt);
;             if constexpr (SP2) {
;             PG8_LDB(B0, 0, 0); PG8_LDB(B1, 0, 1); PG8_SCHED; PG8_LDA(At, 0, 0); PG8_STAGE(PG8_SA(1, 1), a1 + hstepA, voffA);
;             PG8_WAIT_V(8); PG8_WAIT_L(0); PG8_BAR; PG8_MMA(0, 0, At, B0); PG8_MMA(0, 1, At, B1); PG8_BAR; PG8_SCHED;
;             PG8_LDA(At, 0, 1); PG8_STAGE(PG8_SB(0, 0), b2, voffB); PG8_STAGE(PG8_SB(0, 1), b2 + hstepB, voffB); PG8_STAGE(PG8_SA(0, 0), a2, voffA);
;             PG8_WAIT_V(8); PG8_WAIT_L(0); PG8_BAR; PG8_MMA(1, 0, At, B0); PG8_MMA(1, 1, At, B1); PG8_BAR; PG8_SCHED;
;             PG8_LDB(B0, 1, 0); PG8_LDB(B1, 1, 1); PG8_SCHED; PG8_LDA(At, 1, 0); PG8_STAGE(PG8_SA(0, 1), a2 + hstepA, voffA);
;             PG8_WAIT_V(8); PG8_WAIT_L(0); PG8_BAR; PG8_MMA(0, 0, At, B0); PG8_MMA(0, 1, At, B1); PG8_BAR; PG8_SCHED;
;             PG8_LDA(At, 1, 1); PG8_STAGE(PG8_SB(1, 0), b3, voffB); PG8_STAGE(PG8_SB(1, 1), b3 + hstepB, voffB); PG8_STAGE(PG8_SA(1, 0), a3, voffA);
;             PG8_WAIT_V(8); PG8_WAIT_L(0); PG8_BAR; PG8_MMA(1, 0, At, B0); PG8_MMA(1, 1, At, B1); PG8_BAR; PG8_SCHED;
.LBB0_1256:
	s_add_u32 s36, s34, 0x10000
	s_addc_u32 s37, s35, 0
	s_cmp_eq_u32 s66, 28
	s_cselect_b32 s88, s57, s36
	s_cselect_b32 s89, s27, s37
	s_cselect_b32 s86, vcc_lo, vcc_hi
	s_cselect_b32 s87, s25, s65
	s_add_u32 s46, s88, 0x8000
	s_addc_u32 s47, s89, 0
	s_add_i32 s96, 0, 0x10000
	v_add_u32_e32 v0, s96, v192
	s_add_i32 s97, 0, 0x14000
	ds_read_b128 v[130:133], v0
	ds_read_b128 v[134:137], v0 offset:1024
	ds_read_b128 v[138:141], v0 offset:2048
	ds_read_b128 v[142:145], v0 offset:3072
	v_add_u32_e32 v0, s97, v192
	ds_read_b128 v[146:149], v0
	ds_read_b128 v[150:153], v0 offset:1024
	ds_read_b128 v[154:157], v0 offset:2048
	ds_read_b128 v[170:173], v0 offset:3072
	v_lshl_add_u64 v[190:191], s[34:35], 0, v[166:167]
	s_add_i32 m0, s48, 0xc000
	ds_read_b128 v[174:177], v193
	ds_read_b128 v[178:181], v193 offset:1024
	ds_read_b128 v[182:185], v193 offset:2048
	ds_read_b128 v[186:189], v193 offset:3072
	ds_read_b128 v[194:197], v193 offset:4096
	ds_read_b128 v[198:201], v193 offset:5120
	ds_read_b128 v[202:205], v193 offset:6144
	ds_read_b128 v[206:209], v193 offset:7168
	global_load_lds_dwordx4 v[190:191], off
	v_lshl_add_u64 v[190:191], s[34:35], 0, v[168:169]
	s_add_i32 m0, s48, 0xe000
	s_nop 0
	global_load_lds_dwordx4 v[190:191], off
	s_waitcnt vmcnt(8)
	s_waitcnt lgkmcnt(0)
	s_barrier
	s_setprio 1
	s_waitcnt lgkmcnt(0)
	v_mfma_f32_16x16x32_bf16 v[126:129], v[130:133], v[174:177], v[126:129]
	v_mfma_f32_16x16x32_bf16 v[122:125], v[138:141], v[174:177], v[122:125]
	v_mfma_f32_16x16x32_bf16 v[118:121], v[130:133], v[182:185], v[118:121]
	v_mfma_f32_16x16x32_bf16 v[114:117], v[138:141], v[182:185], v[114:117]
	v_mfma_f32_16x16x32_bf16 v[110:113], v[130:133], v[194:197], v[110:113]
	v_mfma_f32_16x16x32_bf16 v[106:109], v[138:141], v[194:197], v[106:109]
	v_mfma_f32_16x16x32_bf16 v[102:105], v[130:133], v[202:205], v[102:105]
	v_mfma_f32_16x16x32_bf16 v[98:101], v[138:141], v[202:205], v[98:101]
	v_mfma_f32_16x16x32_bf16 v[126:129], v[134:137], v[178:181], v[126:129]
	v_mfma_f32_16x16x32_bf16 v[122:125], v[142:145], v[178:181], v[122:125]
	v_mfma_f32_16x16x32_bf16 v[118:121], v[134:137], v[186:189], v[118:121]
	v_mfma_f32_16x16x32_bf16 v[114:117], v[142:145], v[186:189], v[114:117]
	v_mfma_f32_16x16x32_bf16 v[110:113], v[134:137], v[198:201], v[110:113]
	v_mfma_f32_16x16x32_bf16 v[106:109], v[142:145], v[198:201], v[106:109]
	v_mfma_f32_16x16x32_bf16 v[102:105], v[134:137], v[206:209], v[102:105]
	v_mfma_f32_16x16x32_bf16 v[98:101], v[142:145], v[206:209], v[98:101]
	s_setprio 0
	s_setprio 1
	v_mfma_f32_16x16x32_bf16 v[30:33], v[146:149], v[174:177], v[30:33]
	v_mfma_f32_16x16x32_bf16 v[46:49], v[154:157], v[174:177], v[46:49]
	v_mfma_f32_16x16x32_bf16 v[26:29], v[146:149], v[182:185], v[26:29]
	v_mfma_f32_16x16x32_bf16 v[34:37], v[154:157], v[182:185], v[34:37]
	v_mfma_f32_16x16x32_bf16 v[94:97], v[146:149], v[194:197], v[94:97]
	v_mfma_f32_16x16x32_bf16 v[90:93], v[154:157], v[194:197], v[90:93]
	v_mfma_f32_16x16x32_bf16 v[86:89], v[146:149], v[202:205], v[86:89]
	v_mfma_f32_16x16x32_bf16 v[82:85], v[154:157], v[202:205], v[82:85]
	v_mfma_f32_16x16x32_bf16 v[30:33], v[150:153], v[178:181], v[30:33]
	v_mfma_f32_16x16x32_bf16 v[46:49], v[170:173], v[178:181], v[46:49]
	v_mfma_f32_16x16x32_bf16 v[26:29], v[150:153], v[186:189], v[26:29]
	v_mfma_f32_16x16x32_bf16 v[34:37], v[170:173], v[186:189], v[34:37]
	s_setprio 2
	s_barrier
	v_mfma_f32_16x16x32_bf16 v[94:97], v[150:153], v[198:201], v[94:97]
	v_mfma_f32_16x16x32_bf16 v[90:93], v[170:173], v[198:201], v[90:93]
	v_mfma_f32_16x16x32_bf16 v[86:89], v[150:153], v[206:209], v[86:89]
	v_mfma_f32_16x16x32_bf16 v[82:85], v[170:173], v[206:209], v[82:85]
	s_setprio 0
	s_nop 0
	s_add_i32 s34, s96, s44
	v_lshl_add_u64 v[190:191], s[86:87], 0, v[162:163]
	s_mov_b32 m0, s34
	ds_read_b128 v[174:177], v193 offset:16384
	ds_read_b128 v[178:181], v193 offset:17408
	ds_read_b128 v[182:185], v193 offset:18432
	ds_read_b128 v[186:189], v193 offset:19456
	ds_read_b128 v[194:197], v193 offset:20480
	ds_read_b128 v[198:201], v193 offset:21504
	ds_read_b128 v[202:205], v193 offset:22528
	ds_read_b128 v[206:209], v193 offset:23552
	global_load_lds_dwordx4 v[190:191], off
	s_add_i32 m0, s34, 0x2000
	s_add_u32 s34, s86, 0x4000
	v_lshl_add_u64 v[190:191], s[86:87], 0, v[158:159]
	s_addc_u32 s35, s87, 0
	s_add_i32 s96, s97, s44
	global_load_lds_dwordx4 v[190:191], off
	v_lshl_add_u64 v[190:191], s[34:35], 0, v[162:163]
	s_mov_b32 m0, s96
	v_lshl_add_u64 v[210:211], s[88:89], 0, v[160:161]
	global_load_lds_dwordx4 v[190:191], off
	v_lshl_add_u64 v[190:191], s[34:35], 0, v[158:159]
	s_add_i32 m0, s96, 0x2000
	s_nop 0
	global_load_lds_dwordx4 v[190:191], off
	v_lshl_add_u64 v[190:191], s[88:89], 0, v[164:165]
	s_mov_b32 m0, s48
	s_nop 0
	global_load_lds_dwordx4 v[190:191], off
	s_mov_b32 m0, s49
	s_nop 0
	global_load_lds_dwordx4 v[210:211], off
	s_waitcnt vmcnt(8)
	s_waitcnt lgkmcnt(0)
	s_barrier
; #define PG8_STAGE(bufoff, gbase, voff) do { _Pragma("unroll") for (int _i = 0; _i < 2; ++_i) \
;         __builtin_amdgcn_global_load_lds((const unsigned*)((const char*)(gbase) + (voff)[_i]), (PG8_LAS unsigned*)(lds + (bufoff) + ldsw + _i * 8192), 16, 0, 0); } while (0)
; #define PG8_LDA(dst, b, h) do { _Pragma("unroll") for (int m = 0; m < 4; ++m) _Pragma("unroll") for (int k = 0; k < 2; ++k) dst[m][k] = *(const PG8_LAS bf16x8*)(lds + PG8_SA(b, h) + aoff + m * 2048 + k * 1024); } while (0)
; #define PG8_LDB(dst, b, h) do { _Pragma("unroll") for (int n = 0; n < 2; ++n) _Pragma("unroll") for (int k = 0; k < 2; ++k) dst[n][k] = *(const PG8_LAS bf16x8*)(lds + PG8_SB(b, h) + boff + n * 2048 + k * 1024); } while (0)
; #define PG8_MMA(ai, bj, At, Bt) do { __builtin_amdgcn_s_setprio(1); _Pragma("unroll") for (int m = 0; m < 4; ++m) _Pragma("unroll") for (int n = 0; n < 2; ++n) _Pragma("unroll") for (int k = 0; k < 2; ++k) \
;         acc[ai][bj][m][n] = __builtin_amdgcn_mfma_f32_16x16x32_bf16(Bt[n][k], At[m][k], acc[ai][bj][m][n], 0, 0, 0); __builtin_amdgcn_s_setprio(0); } while (0)
; #define PG8_WAIT_V(n) asm volatile("s_waitcnt vmcnt(" #n ")" ::: "memory")
; #define PG8_WAIT_L(n) asm volatile("s_waitcnt lgkmcnt(" #n ")" ::: "memory")
; #define PG8_BAR __builtin_amdgcn_s_barrier()
; #define PG8_SCHED __builtin_amdgcn_sched_barrier(0)
;     ...
;             PG8_LDB(B0, 0, 0); PG8_LDB(B1, 0, 1); PG8_SCHED; PG8_LDA(At, 0, 0); PG8_STAGE(PG8_SA(1, 1), a1 + hstepA, voffA);
;             PG8_WAIT_V(8); PG8_WAIT_L(0); PG8_BAR; PG8_MMA(0, 0, At, B0); PG8_MMA(0, 1, At, B1); PG8_BAR; PG8_SCHED;
;             PG8_LDA(At, 0, 1); PG8_STAGE(PG8_SB(0, 0), b2, voffB); PG8_STAGE(PG8_SB(0, 1), b2 + hstepB, voffB); PG8_STAGE(PG8_SA(0, 0), a2, voffA);
;             PG8_WAIT_V(8); PG8_WAIT_L(0); PG8_BAR; PG8_MMA(1, 0, At, B0); PG8_MMA(1, 1, At, B1); PG8_BAR; PG8_SCHED;
;             PG8_LDB(B0, 1, 0); PG8_LDB(B1, 1, 1); PG8_SCHED; PG8_LDA(At, 1, 0); PG8_STAGE(PG8_SA(0, 1), a2 + hstepA, voffA);
;             PG8_WAIT_V(8); PG8_WAIT_L(0); PG8_BAR; PG8_MMA(0, 0, At, B0); PG8_MMA(0, 1, At, B1); PG8_BAR; PG8_SCHED;
;             PG8_LDA(At, 1, 1); PG8_STAGE(PG8_SB(1, 0), b3, voffB); PG8_STAGE(PG8_SB(1, 1), b3 + hstepB, voffB); PG8_STAGE(PG8_SA(1, 0), a3, voffA);
;             PG8_WAIT_V(8); PG8_WAIT_L(0); PG8_BAR; PG8_MMA(1, 0, At, B0); PG8_MMA(1, 1, At, B1); PG8_BAR; PG8_SCHED;
	s_setprio 1
	s_waitcnt lgkmcnt(0)
	v_mfma_f32_16x16x32_bf16 v[78:81], v[130:133], v[174:177], v[78:81]
	v_mfma_f32_16x16x32_bf16 v[74:77], v[138:141], v[174:177], v[74:77]
	v_mfma_f32_16x16x32_bf16 v[70:73], v[130:133], v[182:185], v[70:73]
	v_mfma_f32_16x16x32_bf16 v[66:69], v[138:141], v[182:185], v[66:69]
	v_mfma_f32_16x16x32_bf16 v[42:45], v[130:133], v[194:197], v[42:45]
	v_mfma_f32_16x16x32_bf16 v[6:9], v[138:141], v[194:197], v[6:9]
	v_mfma_f32_16x16x32_bf16 v[38:41], v[130:133], v[202:205], v[38:41]
	v_mfma_f32_16x16x32_bf16 v[2:5], v[138:141], v[202:205], v[2:5]
	v_mfma_f32_16x16x32_bf16 v[78:81], v[134:137], v[178:181], v[78:81]
	v_mfma_f32_16x16x32_bf16 v[74:77], v[142:145], v[178:181], v[74:77]
	v_mfma_f32_16x16x32_bf16 v[70:73], v[134:137], v[186:189], v[70:73]
	v_mfma_f32_16x16x32_bf16 v[66:69], v[142:145], v[186:189], v[66:69]
	v_mfma_f32_16x16x32_bf16 v[42:45], v[134:137], v[198:201], v[42:45]
	v_mfma_f32_16x16x32_bf16 v[6:9], v[142:145], v[198:201], v[6:9]
	v_mfma_f32_16x16x32_bf16 v[38:41], v[134:137], v[206:209], v[38:41]
	v_mfma_f32_16x16x32_bf16 v[2:5], v[142:145], v[206:209], v[2:5]
	s_setprio 0
	s_setprio 1
	v_mfma_f32_16x16x32_bf16 v[62:65], v[146:149], v[174:177], v[62:65]
	v_mfma_f32_16x16x32_bf16 v[58:61], v[154:157], v[174:177], v[58:61]
	v_mfma_f32_16x16x32_bf16 v[54:57], v[146:149], v[182:185], v[54:57]
	v_mfma_f32_16x16x32_bf16 v[50:53], v[154:157], v[182:185], v[50:53]
	v_mfma_f32_16x16x32_bf16 v[22:25], v[146:149], v[194:197], v[22:25]
	v_mfma_f32_16x16x32_bf16 v[18:21], v[154:157], v[194:197], v[18:21]
	v_mfma_f32_16x16x32_bf16 v[14:17], v[146:149], v[202:205], v[14:17]
	v_mfma_f32_16x16x32_bf16 v[10:13], v[154:157], v[202:205], v[10:13]
	v_mfma_f32_16x16x32_bf16 v[62:65], v[150:153], v[178:181], v[62:65]
	v_mfma_f32_16x16x32_bf16 v[58:61], v[170:173], v[178:181], v[58:61]
	v_mfma_f32_16x16x32_bf16 v[54:57], v[150:153], v[186:189], v[54:57]
	v_mfma_f32_16x16x32_bf16 v[50:53], v[170:173], v[186:189], v[50:53]
	s_setprio 2
	s_barrier
	v_mfma_f32_16x16x32_bf16 v[22:25], v[150:153], v[198:201], v[22:25]
	v_mfma_f32_16x16x32_bf16 v[18:21], v[170:173], v[198:201], v[18:21]
	v_mfma_f32_16x16x32_bf16 v[14:17], v[150:153], v[206:209], v[14:17]
	v_mfma_f32_16x16x32_bf16 v[10:13], v[170:173], v[206:209], v[10:13]
	s_setprio 0
	s_nop 0
	s_add_i32 s88, 0, 0x18000
	v_add_u32_e32 v0, s88, v192
	s_add_i32 s89, 0, 0x1c000
	ds_read_b128 v[130:133], v0
	ds_read_b128 v[134:137], v0 offset:1024
	ds_read_b128 v[138:141], v0 offset:2048
	ds_read_b128 v[142:145], v0 offset:3072
	v_add_u32_e32 v0, s89, v192
	ds_read_b128 v[146:149], v0
	ds_read_b128 v[150:153], v0 offset:1024
	ds_read_b128 v[154:157], v0 offset:2048
	ds_read_b128 v[170:173], v0 offset:3072
	s_mov_b32 m0, s51
	v_lshl_add_u64 v[190:191], v[190:191], 0, s[58:59]
	ds_read_b128 v[174:177], v193 offset:32768
	ds_read_b128 v[178:181], v193 offset:33792
	ds_read_b128 v[182:185], v193 offset:34816
	ds_read_b128 v[186:189], v193 offset:35840
	ds_read_b128 v[194:197], v193 offset:36864
	ds_read_b128 v[198:201], v193 offset:37888
	ds_read_b128 v[202:205], v193 offset:38912
	ds_read_b128 v[206:209], v193 offset:39936
	global_load_lds_dwordx4 v[190:191], off
	v_lshl_add_u64 v[190:191], v[210:211], 0, s[58:59]
	s_mov_b32 m0, s54
	s_nop 0
	global_load_lds_dwordx4 v[190:191], off
	s_waitcnt vmcnt(8)
	s_waitcnt lgkmcnt(0)
	s_barrier
	s_setprio 1
	s_waitcnt lgkmcnt(0)
	v_mfma_f32_16x16x32_bf16 v[126:129], v[130:133], v[174:177], v[126:129]
	v_mfma_f32_16x16x32_bf16 v[122:125], v[138:141], v[174:177], v[122:125]
	v_mfma_f32_16x16x32_bf16 v[118:121], v[130:133], v[182:185], v[118:121]
	v_mfma_f32_16x16x32_bf16 v[114:117], v[138:141], v[182:185], v[114:117]
	v_mfma_f32_16x16x32_bf16 v[110:113], v[130:133], v[194:197], v[110:113]
	v_mfma_f32_16x16x32_bf16 v[106:109], v[138:141], v[194:197], v[106:109]
	v_mfma_f32_16x16x32_bf16 v[102:105], v[130:133], v[202:205], v[102:105]
	v_mfma_f32_16x16x32_bf16 v[98:101], v[138:141], v[202:205], v[98:101]
	v_mfma_f32_16x16x32_bf16 v[126:129], v[134:137], v[178:181], v[126:129]
	v_mfma_f32_16x16x32_bf16 v[122:125], v[142:145], v[178:181], v[122:125]
	v_mfma_f32_16x16x32_bf16 v[118:121], v[134:137], v[186:189], v[118:121]
	v_mfma_f32_16x16x32_bf16 v[114:117], v[142:145], v[186:189], v[114:117]
	v_mfma_f32_16x16x32_bf16 v[110:113], v[134:137], v[198:201], v[110:113]
	v_mfma_f32_16x16x32_bf16 v[106:109], v[142:145], v[198:201], v[106:109]
	v_mfma_f32_16x16x32_bf16 v[102:105], v[134:137], v[206:209], v[102:105]
	v_mfma_f32_16x16x32_bf16 v[98:101], v[142:145], v[206:209], v[98:101]
	s_setprio 0
	s_setprio 1
	v_mfma_f32_16x16x32_bf16 v[30:33], v[146:149], v[174:177], v[30:33]
	v_mfma_f32_16x16x32_bf16 v[46:49], v[154:157], v[174:177], v[46:49]
	v_mfma_f32_16x16x32_bf16 v[26:29], v[146:149], v[182:185], v[26:29]
	v_mfma_f32_16x16x32_bf16 v[34:37], v[154:157], v[182:185], v[34:37]
	v_mfma_f32_16x16x32_bf16 v[94:97], v[146:149], v[194:197], v[94:97]
	v_mfma_f32_16x16x32_bf16 v[90:93], v[154:157], v[194:197], v[90:93]
	v_mfma_f32_16x16x32_bf16 v[86:89], v[146:149], v[202:205], v[86:89]
	v_mfma_f32_16x16x32_bf16 v[82:85], v[154:157], v[202:205], v[82:85]
	v_mfma_f32_16x16x32_bf16 v[30:33], v[150:153], v[178:181], v[30:33]
	v_mfma_f32_16x16x32_bf16 v[46:49], v[170:173], v[178:181], v[46:49]
	v_mfma_f32_16x16x32_bf16 v[26:29], v[150:153], v[186:189], v[26:29]
	v_mfma_f32_16x16x32_bf16 v[34:37], v[170:173], v[186:189], v[34:37]
	s_setprio 2
	s_barrier
; #define PG8_STAGE(bufoff, gbase, voff) do { _Pragma("unroll") for (int _i = 0; _i < 2; ++_i) \
;         __builtin_amdgcn_global_load_lds((const unsigned*)((const char*)(gbase) + (voff)[_i]), (PG8_LAS unsigned*)(lds + (bufoff) + ldsw + _i * 8192), 16, 0, 0); } while (0)
; #define PG8_LDA(dst, b, h) do { _Pragma("unroll") for (int m = 0; m < 4; ++m) _Pragma("unroll") for (int k = 0; k < 2; ++k) dst[m][k] = *(const PG8_LAS bf16x8*)(lds + PG8_SA(b, h) + aoff + m * 2048 + k * 1024); } while (0)
; #define PG8_LDB(dst, b, h) do { _Pragma("unroll") for (int n = 0; n < 2; ++n) _Pragma("unroll") for (int k = 0; k < 2; ++k) dst[n][k] = *(const PG8_LAS bf16x8*)(lds + PG8_SB(b, h) + boff + n * 2048 + k * 1024); } while (0)
; #define PG8_WAIT_V(n) asm volatile("s_waitcnt vmcnt(" #n ")" ::: "memory")
; #define PG8_WAIT_L(n) asm volatile("s_waitcnt lgkmcnt(" #n ")" ::: "memory")
;     ...
;         for (int t = 0; t < nt; t += 2) {
;             const bool last = (t == nt - 2);
;             const char* a1 = cA + (ptrdiff_t)(t + 1) * kstepA;
;             const char* a2 = last ? nA : cA + (ptrdiff_t)(t + 2) * kstepA; const char* b2 = last ? nB : cB + (ptrdiff_t)(t + 2) * kstep;
;             const char* a3 = a2 + kstepA; const char* b3 = b2 + kstep;
;             if (last && has_next) S.a_ready(nxt);
;             if constexpr (SP2) {
;             PG8_LDB(B0, 0, 0); PG8_LDB(B1, 0, 1); PG8_SCHED; PG8_LDA(At, 0, 0); PG8_STAGE(PG8_SA(1, 1), a1 + hstepA, voffA);
;             PG8_WAIT_V(8); PG8_WAIT_L(0); PG8_BAR; PG8_MMA(0, 0, At, B0); PG8_MMA(0, 1, At, B1); PG8_BAR; PG8_SCHED;
;             PG8_LDA(At, 0, 1); PG8_STAGE(PG8_SB(0, 0), b2, voffB); PG8_STAGE(PG8_SB(0, 1), b2 + hstepB, voffB); PG8_STAGE(PG8_SA(0, 0), a2, voffA);
;             PG8_WAIT_V(8); PG8_WAIT_L(0); PG8_BAR; PG8_MMA(1, 0, At, B0); PG8_MMA(1, 1, At, B1); PG8_BAR; PG8_SCHED;
;             PG8_LDB(B0, 1, 0); PG8_LDB(B1, 1, 1); PG8_SCHED; PG8_LDA(At, 1, 0); PG8_STAGE(PG8_SA(0, 1), a2 + hstepA, voffA);
;             PG8_WAIT_V(8); PG8_WAIT_L(0); PG8_BAR; PG8_MMA(0, 0, At, B0); PG8_MMA(0, 1, At, B1); PG8_BAR; PG8_SCHED;
;             PG8_LDA(At, 1, 1); PG8_STAGE(PG8_SB(1, 0), b3, voffB); PG8_STAGE(PG8_SB(1, 1), b3 + hstepB, voffB); PG8_STAGE(PG8_SA(1, 0), a3, voffA);
;             PG8_WAIT_V(8); PG8_WAIT_L(0); PG8_BAR; PG8_MMA(1, 0, At, B0); PG8_MMA(1, 1, At, B1); PG8_BAR; PG8_SCHED;
	v_mfma_f32_16x16x32_bf16 v[94:97], v[150:153], v[198:201], v[94:97]
	v_mfma_f32_16x16x32_bf16 v[90:93], v[170:173], v[198:201], v[90:93]
	v_mfma_f32_16x16x32_bf16 v[86:89], v[150:153], v[206:209], v[86:89]
	v_mfma_f32_16x16x32_bf16 v[82:85], v[170:173], v[206:209], v[82:85]
	s_setprio 0
	s_nop 0
	s_add_u32 s34, s86, 0x8000
	s_addc_u32 s35, s87, 0
	s_add_i32 s88, s88, s44
	v_lshl_add_u64 v[190:191], s[34:35], 0, v[162:163]
	s_mov_b32 m0, s88
	ds_read_b128 v[174:177], v193 offset:49152
	ds_read_b128 v[178:181], v193 offset:50176
	ds_read_b128 v[182:185], v193 offset:51200
	ds_read_b128 v[186:189], v193 offset:52224
	ds_read_b128 v[194:197], v193 offset:53248
	ds_read_b128 v[198:201], v193 offset:54272
	ds_read_b128 v[202:205], v193 offset:55296
	ds_read_b128 v[206:209], v193 offset:56320
	global_load_lds_dwordx4 v[190:191], off
	s_add_i32 m0, s88, 0x2000
	v_lshl_add_u64 v[190:191], s[34:35], 0, v[158:159]
	s_add_u32 s34, s86, 0xc000
	s_addc_u32 s35, s87, 0
	s_add_i32 s86, s89, s44
	global_load_lds_dwordx4 v[190:191], off
	v_lshl_add_u64 v[190:191], s[34:35], 0, v[162:163]
	s_mov_b32 m0, s86
	s_nop 0
	global_load_lds_dwordx4 v[190:191], off
	v_lshl_add_u64 v[190:191], s[34:35], 0, v[158:159]
	s_add_i32 m0, s86, 0x2000
	s_nop 0
	global_load_lds_dwordx4 v[190:191], off
	v_lshl_add_u64 v[190:191], s[46:47], 0, v[164:165]
	s_mov_b32 m0, s85
	s_nop 0
	global_load_lds_dwordx4 v[190:191], off
	v_lshl_add_u64 v[190:191], s[46:47], 0, v[160:161]
	s_mov_b32 m0, s90
	s_nop 0
	global_load_lds_dwordx4 v[190:191], off
	s_waitcnt vmcnt(8)
	s_waitcnt lgkmcnt(0)
	s_barrier
	s_setprio 1
	s_waitcnt lgkmcnt(0)
	v_mfma_f32_16x16x32_bf16 v[78:81], v[130:133], v[174:177], v[78:81]
	v_mfma_f32_16x16x32_bf16 v[74:77], v[138:141], v[174:177], v[74:77]
	v_mfma_f32_16x16x32_bf16 v[70:73], v[130:133], v[182:185], v[70:73]
	v_mfma_f32_16x16x32_bf16 v[66:69], v[138:141], v[182:185], v[66:69]
	v_mfma_f32_16x16x32_bf16 v[42:45], v[130:133], v[194:197], v[42:45]
	v_mfma_f32_16x16x32_bf16 v[6:9], v[138:141], v[194:197], v[6:9]
	v_mfma_f32_16x16x32_bf16 v[38:41], v[130:133], v[202:205], v[38:41]
	v_mfma_f32_16x16x32_bf16 v[2:5], v[138:141], v[202:205], v[2:5]
	v_mfma_f32_16x16x32_bf16 v[78:81], v[134:137], v[178:181], v[78:81]
	v_mfma_f32_16x16x32_bf16 v[74:77], v[142:145], v[178:181], v[74:77]
	v_mfma_f32_16x16x32_bf16 v[70:73], v[134:137], v[186:189], v[70:73]
	v_mfma_f32_16x16x32_bf16 v[66:69], v[142:145], v[186:189], v[66:69]
	v_mfma_f32_16x16x32_bf16 v[42:45], v[134:137], v[198:201], v[42:45]
	v_mfma_f32_16x16x32_bf16 v[6:9], v[142:145], v[198:201], v[6:9]
	v_mfma_f32_16x16x32_bf16 v[38:41], v[134:137], v[206:209], v[38:41]
	v_mfma_f32_16x16x32_bf16 v[2:5], v[142:145], v[206:209], v[2:5]
	s_setprio 0
	s_setprio 1
	v_mfma_f32_16x16x32_bf16 v[62:65], v[146:149], v[174:177], v[62:65]
	v_mfma_f32_16x16x32_bf16 v[58:61], v[154:157], v[174:177], v[58:61]
	v_mfma_f32_16x16x32_bf16 v[54:57], v[146:149], v[182:185], v[54:57]
	v_mfma_f32_16x16x32_bf16 v[50:53], v[154:157], v[182:185], v[50:53]
	v_mfma_f32_16x16x32_bf16 v[22:25], v[146:149], v[194:197], v[22:25]
	v_mfma_f32_16x16x32_bf16 v[18:21], v[154:157], v[194:197], v[18:21]
	v_mfma_f32_16x16x32_bf16 v[14:17], v[146:149], v[202:205], v[14:17]
	v_mfma_f32_16x16x32_bf16 v[10:13], v[154:157], v[202:205], v[10:13]
	v_mfma_f32_16x16x32_bf16 v[62:65], v[150:153], v[178:181], v[62:65]
	v_mfma_f32_16x16x32_bf16 v[58:61], v[170:173], v[178:181], v[58:61]
	v_mfma_f32_16x16x32_bf16 v[54:57], v[150:153], v[186:189], v[54:57]
	v_mfma_f32_16x16x32_bf16 v[50:53], v[170:173], v[186:189], v[50:53]
	s_setprio 2
	s_barrier
	v_mfma_f32_16x16x32_bf16 v[22:25], v[150:153], v[198:201], v[22:25]
	v_mfma_f32_16x16x32_bf16 v[18:21], v[170:173], v[198:201], v[18:21]
	v_mfma_f32_16x16x32_bf16 v[14:17], v[150:153], v[206:209], v[14:17]
	v_mfma_f32_16x16x32_bf16 v[10:13], v[170:173], v[206:209], v[10:13]
	s_setprio 0
	s_nop 0
	s_add_i32 s66, s66, 2
	s_add_u32 vcc_hi, vcc_hi, 0x10000
	s_addc_u32 s65, s65, 0
	s_cmp_gt_u32 s66, 29
	s_mov_b64 s[34:35], s[36:37]
	s_cbranch_scc0 .LBB0_1256
	s_and_b64 vcc, exec, s[18:19]
	s_cbranch_vccz .LBB0_1259
	s_barrier

; #define PG8_STAGE(bufoff, gbase, voff) do { _Pragma("unroll") for (int _i = 0; _i < 2; ++_i) \
;         __builtin_amdgcn_global_load_lds((const unsigned*)((const char*)(gbase) + (voff)[_i]), (PG8_LAS unsigned*)(lds + (bufoff) + ldsw + _i * 8192), 16, 0, 0); } while (0)
; #define PG8_LDA(dst, b, h) do { _Pragma("unroll") for (int m = 0; m < 4; ++m) _Pragma("unroll") for (int k = 0; k < 2; ++k) dst[m][k] = *(const PG8_LAS bf16x8*)(lds + PG8_SA(b, h) + aoff + m * 2048 + k * 1024); } while (0)
; #define PG8_LDB(dst, b, h) do { _Pragma("unroll") for (int n = 0; n < 2; ++n) _Pragma("unroll") for (int k = 0; k < 2; ++k) dst[n][k] = *(const PG8_LAS bf16x8*)(lds + PG8_SB(b, h) + boff + n * 2048 + k * 1024); } while (0)
; #define PG8_WAIT_V(n) asm volatile("s_waitcnt vmcnt(" #n ")" ::: "memory")
; #define PG8_WAIT_L(n) asm volatile("s_waitcnt lgkmcnt(" #n ")" ::: "memory")
;     ...
;         for (int t = 0; t < nt; t += 2) {
;             const bool last = (t == nt - 2);
;             const char* a1 = cA + (ptrdiff_t)(t + 1) * kstepA;
;             const char* a2 = last ? nA : cA + (ptrdiff_t)(t + 2) * kstepA; const char* b2 = last ? nB : cB + (ptrdiff_t)(t + 2) * kstep;
;             const char* a3 = a2 + kstepA; const char* b3 = b2 + kstep;
;             if (last && has_next) S.a_ready(nxt);
;             if constexpr (SP2) {
;             PG8_LDB(B0, 0, 0); PG8_LDB(B1, 0, 1); PG8_SCHED; PG8_LDA(At, 0, 0); PG8_STAGE(PG8_SA(1, 1), a1 + hstepA, voffA);
;             PG8_WAIT_V(8); PG8_WAIT_L(0); PG8_BAR; PG8_MMA(0, 0, At, B0); PG8_MMA(0, 1, At, B1); PG8_BAR; PG8_SCHED;
;             PG8_LDA(At, 0, 1); PG8_STAGE(PG8_SB(0, 0), b2, voffB); PG8_STAGE(PG8_SB(0, 1), b2 + hstepB, voffB); PG8_STAGE(PG8_SA(0, 0), a2, voffA);
;             PG8_WAIT_V(8); PG8_WAIT_L(0); PG8_BAR; PG8_MMA(1, 0, At, B0); PG8_MMA(1, 1, At, B1); PG8_BAR; PG8_SCHED;
;             PG8_LDB(B0, 1, 0); PG8_LDB(B1, 1, 1); PG8_SCHED; PG8_LDA(At, 1, 0); PG8_STAGE(PG8_SA(0, 1), a2 + hstepA, voffA);
;             PG8_WAIT_V(8); PG8_WAIT_L(0); PG8_BAR; PG8_MMA(0, 0, At, B0); PG8_MMA(0, 1, At, B1); PG8_BAR; PG8_SCHED;
;             PG8_LDA(At, 1, 1); PG8_STAGE(PG8_SB(1, 0), b3, voffB); PG8_STAGE(PG8_SB(1, 1), b3 + hstepB, voffB); PG8_STAGE(PG8_SA(1, 0), a3, voffA);
;             PG8_WAIT_V(8); PG8_WAIT_L(0); PG8_BAR; PG8_MMA(1, 0, At, B0); PG8_MMA(1, 1, At, B1); PG8_BAR; PG8_SCHED;
.LBB0_1444:
	s_or_b32 s44, s56, 1
	s_lshl_b64 s[34:35], s[44:45], 15
	s_sub_u32 s34, 0, s34
	s_subb_u32 s35, 0, s35
	s_add_u32 s44, s28, s34
	s_addc_u32 s65, s29, s35
	s_add_u32 s34, s30, 0xffff8000
	s_addc_u32 s35, s31, -1
	s_add_i32 s66, 0, 0x10000
	v_add_u32_e32 v0, s66, v230
	s_add_i32 s90, 0, 0x14000
	s_waitcnt lgkmcnt(0)
	ds_read_b128 v[130:133], v0
	ds_read_b128 v[134:137], v0 offset:1024
	ds_read_b128 v[138:141], v0 offset:2048
	ds_read_b128 v[142:145], v0 offset:3072
	v_add_u32_e32 v0, s90, v230
	ds_read_b128 v[146:149], v0
	ds_read_b128 v[150:153], v0 offset:1024
	ds_read_b128 v[154:157], v0 offset:2048
	ds_read_b128 v[158:161], v0 offset:3072
	s_add_u32 s88, s44, 0x4000
	s_addc_u32 s89, s65, 0
	v_lshl_add_u64 v[202:203], s[88:89], 0, v[194:195]
	s_add_i32 m0, s46, 0xc000
	ds_read_b128 v[162:165], v231
	ds_read_b128 v[166:169], v231 offset:1024
	ds_read_b128 v[170:173], v231 offset:2048
	ds_read_b128 v[174:177], v231 offset:3072
	ds_read_b128 v[178:181], v231 offset:4096
	ds_read_b128 v[182:185], v231 offset:5120
	ds_read_b128 v[186:189], v231 offset:6144
	ds_read_b128 v[190:193], v231 offset:7168
	global_load_lds_dwordx4 v[202:203], off
	v_lshl_add_u64 v[202:203], s[88:89], 0, v[198:199]
	s_add_i32 m0, s46, 0xe000
	s_nop 0
	global_load_lds_dwordx4 v[202:203], off
	s_waitcnt vmcnt(8)
	s_waitcnt lgkmcnt(0)
	s_barrier
	s_setprio 1
	s_waitcnt lgkmcnt(0)
	v_mfma_f32_16x16x32_bf16 v[126:129], v[130:133], v[162:165], v[126:129]
	v_mfma_f32_16x16x32_bf16 v[122:125], v[138:141], v[162:165], v[122:125]
	v_mfma_f32_16x16x32_bf16 v[110:113], v[130:133], v[170:173], v[110:113]
	v_mfma_f32_16x16x32_bf16 v[106:109], v[138:141], v[170:173], v[106:109]
	v_mfma_f32_16x16x32_bf16 v[94:97], v[130:133], v[178:181], v[94:97]
	v_mfma_f32_16x16x32_bf16 v[90:93], v[138:141], v[178:181], v[90:93]
	v_mfma_f32_16x16x32_bf16 v[78:81], v[130:133], v[186:189], v[78:81]
	v_mfma_f32_16x16x32_bf16 v[74:77], v[138:141], v[186:189], v[74:77]
	v_mfma_f32_16x16x32_bf16 v[126:129], v[134:137], v[166:169], v[126:129]
	v_mfma_f32_16x16x32_bf16 v[122:125], v[142:145], v[166:169], v[122:125]
	v_mfma_f32_16x16x32_bf16 v[110:113], v[134:137], v[174:177], v[110:113]
	v_mfma_f32_16x16x32_bf16 v[106:109], v[142:145], v[174:177], v[106:109]
	v_mfma_f32_16x16x32_bf16 v[94:97], v[134:137], v[182:185], v[94:97]
	v_mfma_f32_16x16x32_bf16 v[90:93], v[142:145], v[182:185], v[90:93]
	v_mfma_f32_16x16x32_bf16 v[78:81], v[134:137], v[190:193], v[78:81]
	v_mfma_f32_16x16x32_bf16 v[74:77], v[142:145], v[190:193], v[74:77]
	s_setprio 0
	s_setprio 1
	v_mfma_f32_16x16x32_bf16 v[118:121], v[146:149], v[162:165], v[118:121]
	v_mfma_f32_16x16x32_bf16 v[114:117], v[154:157], v[162:165], v[114:117]
	v_mfma_f32_16x16x32_bf16 v[102:105], v[146:149], v[170:173], v[102:105]
	v_mfma_f32_16x16x32_bf16 v[98:101], v[154:157], v[170:173], v[98:101]
	v_mfma_f32_16x16x32_bf16 v[86:89], v[146:149], v[178:181], v[86:89]
	v_mfma_f32_16x16x32_bf16 v[82:85], v[154:157], v[178:181], v[82:85]
	v_mfma_f32_16x16x32_bf16 v[70:73], v[146:149], v[186:189], v[70:73]
	v_mfma_f32_16x16x32_bf16 v[66:69], v[154:157], v[186:189], v[66:69]
	v_mfma_f32_16x16x32_bf16 v[118:121], v[150:153], v[166:169], v[118:121]
	v_mfma_f32_16x16x32_bf16 v[114:117], v[158:161], v[166:169], v[114:117]
	v_mfma_f32_16x16x32_bf16 v[102:105], v[150:153], v[174:177], v[102:105]
	v_mfma_f32_16x16x32_bf16 v[98:101], v[158:161], v[174:177], v[98:101]
	s_setprio 2
	s_barrier
	v_mfma_f32_16x16x32_bf16 v[86:89], v[150:153], v[182:185], v[86:89]
	v_mfma_f32_16x16x32_bf16 v[82:85], v[158:161], v[182:185], v[82:85]
	v_mfma_f32_16x16x32_bf16 v[70:73], v[150:153], v[190:193], v[70:73]
	v_mfma_f32_16x16x32_bf16 v[66:69], v[158:161], v[190:193], v[66:69]
	s_setprio 0
	s_nop 0
	s_add_i32 s44, s66, s41
	v_lshl_add_u64 v[202:203], s[8:9], 0, v[196:197]
	s_mov_b32 m0, s44
	ds_read_b128 v[162:165], v231 offset:16384
	ds_read_b128 v[166:169], v231 offset:17408
	ds_read_b128 v[170:173], v231 offset:18432
	ds_read_b128 v[174:177], v231 offset:19456
	ds_read_b128 v[178:181], v231 offset:20480
	ds_read_b128 v[182:185], v231 offset:21504
	ds_read_b128 v[186:189], v231 offset:22528
	ds_read_b128 v[190:193], v231 offset:23552
	global_load_lds_dwordx4 v[202:203], off
	s_add_i32 m0, s44, 0x2000
	s_add_u32 s88, s8, 0x4000
	v_lshl_add_u64 v[202:203], s[8:9], 0, v[200:201]
	s_addc_u32 s89, s9, 0
	s_add_i32 s44, s90, s41
	global_load_lds_dwordx4 v[202:203], off
	v_lshl_add_u64 v[202:203], s[88:89], 0, v[196:197]
	s_mov_b32 m0, s44
	s_nop 0
	global_load_lds_dwordx4 v[202:203], off
	v_lshl_add_u64 v[202:203], s[88:89], 0, v[200:201]
	s_add_i32 m0, s44, 0x2000
	s_nop 0
	global_load_lds_dwordx4 v[202:203], off
	v_lshl_add_u64 v[202:203], s[30:31], 0, v[194:195]
	s_mov_b32 m0, s46
	s_nop 0
	global_load_lds_dwordx4 v[202:203], off
	v_lshl_add_u64 v[202:203], s[30:31], 0, v[198:199]
	s_mov_b32 m0, s47
	s_nop 0
	global_load_lds_dwordx4 v[202:203], off
	s_waitcnt vmcnt(8)
	s_waitcnt lgkmcnt(0)
	s_barrier
; #define PG8_STAGE(bufoff, gbase, voff) do { _Pragma("unroll") for (int _i = 0; _i < 2; ++_i) \
;         __builtin_amdgcn_global_load_lds((const unsigned*)((const char*)(gbase) + (voff)[_i]), (PG8_LAS unsigned*)(lds + (bufoff) + ldsw + _i * 8192), 16, 0, 0); } while (0)
; #define PG8_LDA(dst, b, h) do { _Pragma("unroll") for (int m = 0; m < 4; ++m) _Pragma("unroll") for (int k = 0; k < 2; ++k) dst[m][k] = *(const PG8_LAS bf16x8*)(lds + PG8_SA(b, h) + aoff + m * 2048 + k * 1024); } while (0)
; #define PG8_LDB(dst, b, h) do { _Pragma("unroll") for (int n = 0; n < 2; ++n) _Pragma("unroll") for (int k = 0; k < 2; ++k) dst[n][k] = *(const PG8_LAS bf16x8*)(lds + PG8_SB(b, h) + boff + n * 2048 + k * 1024); } while (0)
; #define PG8_MMA(ai, bj, At, Bt) do { __builtin_amdgcn_s_setprio(1); _Pragma("unroll") for (int m = 0; m < 4; ++m) _Pragma("unroll") for (int n = 0; n < 2; ++n) _Pragma("unroll") for (int k = 0; k < 2; ++k) \
;         acc[ai][bj][m][n] = __builtin_amdgcn_mfma_f32_16x16x32_bf16(Bt[n][k], At[m][k], acc[ai][bj][m][n], 0, 0, 0); __builtin_amdgcn_s_setprio(0); } while (0)
; #define PG8_WAIT_V(n) asm volatile("s_waitcnt vmcnt(" #n ")" ::: "memory")
; #define PG8_WAIT_L(n) asm volatile("s_waitcnt lgkmcnt(" #n ")" ::: "memory")
; #define PG8_BAR __builtin_amdgcn_s_barrier()
; #define PG8_SCHED __builtin_amdgcn_sched_barrier(0)
;     ...
;             PG8_LDB(B0, 0, 0); PG8_LDB(B1, 0, 1); PG8_SCHED; PG8_LDA(At, 0, 0); PG8_STAGE(PG8_SA(1, 1), a1 + hstepA, voffA);
;             PG8_WAIT_V(8); PG8_WAIT_L(0); PG8_BAR; PG8_MMA(0, 0, At, B0); PG8_MMA(0, 1, At, B1); PG8_BAR; PG8_SCHED;
;             PG8_LDA(At, 0, 1); PG8_STAGE(PG8_SB(0, 0), b2, voffB); PG8_STAGE(PG8_SB(0, 1), b2 + hstepB, voffB); PG8_STAGE(PG8_SA(0, 0), a2, voffA);
;             PG8_WAIT_V(8); PG8_WAIT_L(0); PG8_BAR; PG8_MMA(1, 0, At, B0); PG8_MMA(1, 1, At, B1); PG8_BAR; PG8_SCHED;
;             PG8_LDB(B0, 1, 0); PG8_LDB(B1, 1, 1); PG8_SCHED; PG8_LDA(At, 1, 0); PG8_STAGE(PG8_SA(0, 1), a2 + hstepA, voffA);
;             PG8_WAIT_V(8); PG8_WAIT_L(0); PG8_BAR; PG8_MMA(0, 0, At, B0); PG8_MMA(0, 1, At, B1); PG8_BAR; PG8_SCHED;
;             PG8_LDA(At, 1, 1); PG8_STAGE(PG8_SB(1, 0), b3, voffB); PG8_STAGE(PG8_SB(1, 1), b3 + hstepB, voffB); PG8_STAGE(PG8_SA(1, 0), a3, voffA);
;             PG8_WAIT_V(8); PG8_WAIT_L(0); PG8_BAR; PG8_MMA(1, 0, At, B0); PG8_MMA(1, 1, At, B1); PG8_BAR; PG8_SCHED;
	s_setprio 1
	s_waitcnt lgkmcnt(0)
	v_mfma_f32_16x16x32_bf16 v[62:65], v[130:133], v[162:165], v[62:65]
	v_mfma_f32_16x16x32_bf16 v[58:61], v[138:141], v[162:165], v[58:61]
	v_mfma_f32_16x16x32_bf16 v[46:49], v[130:133], v[170:173], v[46:49]
	v_mfma_f32_16x16x32_bf16 v[42:45], v[138:141], v[170:173], v[42:45]
	v_mfma_f32_16x16x32_bf16 v[30:33], v[130:133], v[178:181], v[30:33]
	v_mfma_f32_16x16x32_bf16 v[26:29], v[138:141], v[178:181], v[26:29]
	v_mfma_f32_16x16x32_bf16 v[14:17], v[130:133], v[186:189], v[14:17]
	v_mfma_f32_16x16x32_bf16 v[10:13], v[138:141], v[186:189], v[10:13]
	v_mfma_f32_16x16x32_bf16 v[62:65], v[134:137], v[166:169], v[62:65]
	v_mfma_f32_16x16x32_bf16 v[58:61], v[142:145], v[166:169], v[58:61]
	v_mfma_f32_16x16x32_bf16 v[46:49], v[134:137], v[174:177], v[46:49]
	v_mfma_f32_16x16x32_bf16 v[42:45], v[142:145], v[174:177], v[42:45]
	v_mfma_f32_16x16x32_bf16 v[30:33], v[134:137], v[182:185], v[30:33]
	v_mfma_f32_16x16x32_bf16 v[26:29], v[142:145], v[182:185], v[26:29]
	v_mfma_f32_16x16x32_bf16 v[14:17], v[134:137], v[190:193], v[14:17]
	v_mfma_f32_16x16x32_bf16 v[10:13], v[142:145], v[190:193], v[10:13]
	s_setprio 0
	s_setprio 1
	v_mfma_f32_16x16x32_bf16 v[54:57], v[146:149], v[162:165], v[54:57]
	v_mfma_f32_16x16x32_bf16 v[50:53], v[154:157], v[162:165], v[50:53]
	v_mfma_f32_16x16x32_bf16 v[38:41], v[146:149], v[170:173], v[38:41]
	v_mfma_f32_16x16x32_bf16 v[34:37], v[154:157], v[170:173], v[34:37]
	v_mfma_f32_16x16x32_bf16 v[22:25], v[146:149], v[178:181], v[22:25]
	v_mfma_f32_16x16x32_bf16 v[18:21], v[154:157], v[178:181], v[18:21]
	v_mfma_f32_16x16x32_bf16 v[6:9], v[146:149], v[186:189], v[6:9]
	v_mfma_f32_16x16x32_bf16 v[2:5], v[154:157], v[186:189], v[2:5]
	v_mfma_f32_16x16x32_bf16 v[54:57], v[150:153], v[166:169], v[54:57]
	v_mfma_f32_16x16x32_bf16 v[50:53], v[158:161], v[166:169], v[50:53]
	v_mfma_f32_16x16x32_bf16 v[38:41], v[150:153], v[174:177], v[38:41]
	v_mfma_f32_16x16x32_bf16 v[34:37], v[158:161], v[174:177], v[34:37]
	s_setprio 2
	s_barrier
	v_mfma_f32_16x16x32_bf16 v[22:25], v[150:153], v[182:185], v[22:25]
	v_mfma_f32_16x16x32_bf16 v[18:21], v[158:161], v[182:185], v[18:21]
	v_mfma_f32_16x16x32_bf16 v[6:9], v[150:153], v[190:193], v[6:9]
	v_mfma_f32_16x16x32_bf16 v[2:5], v[158:161], v[190:193], v[2:5]
	s_setprio 0
	s_nop 0
	s_add_i32 s44, 0, 0x18000
	v_add_u32_e32 v0, s44, v230
	s_add_i32 s65, 0, 0x1c000
	ds_read_b128 v[130:133], v0
	ds_read_b128 v[134:137], v0 offset:1024
	ds_read_b128 v[138:141], v0 offset:2048
	ds_read_b128 v[142:145], v0 offset:3072
	v_add_u32_e32 v0, s65, v230
	ds_read_b128 v[146:149], v0
	ds_read_b128 v[150:153], v0 offset:1024
	ds_read_b128 v[154:157], v0 offset:2048
	ds_read_b128 v[158:161], v0 offset:3072
	s_add_u32 s30, s30, 0x4000
	s_addc_u32 s31, s31, 0
	s_mov_b32 m0, s48
	v_lshl_add_u64 v[202:203], s[30:31], 0, v[194:195]
	ds_read_b128 v[162:165], v231 offset:32768
	ds_read_b128 v[166:169], v231 offset:33792
	ds_read_b128 v[170:173], v231 offset:34816
	ds_read_b128 v[174:177], v231 offset:35840
	ds_read_b128 v[178:181], v231 offset:36864
	ds_read_b128 v[182:185], v231 offset:37888
	ds_read_b128 v[186:189], v231 offset:38912
	ds_read_b128 v[190:193], v231 offset:39936
	global_load_lds_dwordx4 v[202:203], off
	v_lshl_add_u64 v[202:203], s[30:31], 0, v[198:199]
	s_mov_b32 m0, s49
	s_nop 0
	global_load_lds_dwordx4 v[202:203], off
	s_waitcnt vmcnt(8)
	s_waitcnt lgkmcnt(0)
	s_barrier
	s_setprio 1
	s_waitcnt lgkmcnt(0)
	v_mfma_f32_16x16x32_bf16 v[126:129], v[130:133], v[162:165], v[126:129]
	v_mfma_f32_16x16x32_bf16 v[122:125], v[138:141], v[162:165], v[122:125]
	v_mfma_f32_16x16x32_bf16 v[110:113], v[130:133], v[170:173], v[110:113]
	v_mfma_f32_16x16x32_bf16 v[106:109], v[138:141], v[170:173], v[106:109]
	v_mfma_f32_16x16x32_bf16 v[94:97], v[130:133], v[178:181], v[94:97]
	v_mfma_f32_16x16x32_bf16 v[90:93], v[138:141], v[178:181], v[90:93]
	v_mfma_f32_16x16x32_bf16 v[78:81], v[130:133], v[186:189], v[78:81]
	v_mfma_f32_16x16x32_bf16 v[74:77], v[138:141], v[186:189], v[74:77]
	v_mfma_f32_16x16x32_bf16 v[126:129], v[134:137], v[166:169], v[126:129]
	v_mfma_f32_16x16x32_bf16 v[122:125], v[142:145], v[166:169], v[122:125]
	v_mfma_f32_16x16x32_bf16 v[110:113], v[134:137], v[174:177], v[110:113]
	v_mfma_f32_16x16x32_bf16 v[106:109], v[142:145], v[174:177], v[106:109]
	v_mfma_f32_16x16x32_bf16 v[94:97], v[134:137], v[182:185], v[94:97]
	v_mfma_f32_16x16x32_bf16 v[90:93], v[142:145], v[182:185], v[90:93]
	v_mfma_f32_16x16x32_bf16 v[78:81], v[134:137], v[190:193], v[78:81]
	v_mfma_f32_16x16x32_bf16 v[74:77], v[142:145], v[190:193], v[74:77]
	s_setprio 0
	s_setprio 1
	v_mfma_f32_16x16x32_bf16 v[118:121], v[146:149], v[162:165], v[118:121]
	v_mfma_f32_16x16x32_bf16 v[114:117], v[154:157], v[162:165], v[114:117]
	v_mfma_f32_16x16x32_bf16 v[102:105], v[146:149], v[170:173], v[102:105]
	v_mfma_f32_16x16x32_bf16 v[98:101], v[154:157], v[170:173], v[98:101]
	v_mfma_f32_16x16x32_bf16 v[86:89], v[146:149], v[178:181], v[86:89]
	v_mfma_f32_16x16x32_bf16 v[82:85], v[154:157], v[178:181], v[82:85]
	v_mfma_f32_16x16x32_bf16 v[70:73], v[146:149], v[186:189], v[70:73]
	v_mfma_f32_16x16x32_bf16 v[66:69], v[154:157], v[186:189], v[66:69]
	v_mfma_f32_16x16x32_bf16 v[118:121], v[150:153], v[166:169], v[118:121]
	v_mfma_f32_16x16x32_bf16 v[114:117], v[158:161], v[166:169], v[114:117]
	v_mfma_f32_16x16x32_bf16 v[102:105], v[150:153], v[174:177], v[102:105]
	v_mfma_f32_16x16x32_bf16 v[98:101], v[158:161], v[174:177], v[98:101]
	s_setprio 2
	s_barrier
; #define PG8_STAGE(bufoff, gbase, voff) do { _Pragma("unroll") for (int _i = 0; _i < 2; ++_i) \
;         __builtin_amdgcn_global_load_lds((const unsigned*)((const char*)(gbase) + (voff)[_i]), (PG8_LAS unsigned*)(lds + (bufoff) + ldsw + _i * 8192), 16, 0, 0); } while (0)
; #define PG8_LDA(dst, b, h) do { _Pragma("unroll") for (int m = 0; m < 4; ++m) _Pragma("unroll") for (int k = 0; k < 2; ++k) dst[m][k] = *(const PG8_LAS bf16x8*)(lds + PG8_SA(b, h) + aoff + m * 2048 + k * 1024); } while (0)
; #define PG8_LDB(dst, b, h) do { _Pragma("unroll") for (int n = 0; n < 2; ++n) _Pragma("unroll") for (int k = 0; k < 2; ++k) dst[n][k] = *(const PG8_LAS bf16x8*)(lds + PG8_SB(b, h) + boff + n * 2048 + k * 1024); } while (0)
; #define PG8_WAIT_V(n) asm volatile("s_waitcnt vmcnt(" #n ")" ::: "memory")
; #define PG8_WAIT_L(n) asm volatile("s_waitcnt lgkmcnt(" #n ")" ::: "memory")
;     ...
;         for (int t = 0; t < nt; t += 2) {
;             const bool last = (t == nt - 2);
;             const char* a1 = cA + (ptrdiff_t)(t + 1) * kstepA;
;             const char* a2 = last ? nA : cA + (ptrdiff_t)(t + 2) * kstepA; const char* b2 = last ? nB : cB + (ptrdiff_t)(t + 2) * kstep;
;             const char* a3 = a2 + kstepA; const char* b3 = b2 + kstep;
;             if (last && has_next) S.a_ready(nxt);
;             if constexpr (SP2) {
;             PG8_LDB(B0, 0, 0); PG8_LDB(B1, 0, 1); PG8_SCHED; PG8_LDA(At, 0, 0); PG8_STAGE(PG8_SA(1, 1), a1 + hstepA, voffA);
;             PG8_WAIT_V(8); PG8_WAIT_L(0); PG8_BAR; PG8_MMA(0, 0, At, B0); PG8_MMA(0, 1, At, B1); PG8_BAR; PG8_SCHED;
;             PG8_LDA(At, 0, 1); PG8_STAGE(PG8_SB(0, 0), b2, voffB); PG8_STAGE(PG8_SB(0, 1), b2 + hstepB, voffB); PG8_STAGE(PG8_SA(0, 0), a2, voffA);
;             PG8_WAIT_V(8); PG8_WAIT_L(0); PG8_BAR; PG8_MMA(1, 0, At, B0); PG8_MMA(1, 1, At, B1); PG8_BAR; PG8_SCHED;
;             PG8_LDB(B0, 1, 0); PG8_LDB(B1, 1, 1); PG8_SCHED; PG8_LDA(At, 1, 0); PG8_STAGE(PG8_SA(0, 1), a2 + hstepA, voffA);
;             PG8_WAIT_V(8); PG8_WAIT_L(0); PG8_BAR; PG8_MMA(0, 0, At, B0); PG8_MMA(0, 1, At, B1); PG8_BAR; PG8_SCHED;
;             PG8_LDA(At, 1, 1); PG8_STAGE(PG8_SB(1, 0), b3, voffB); PG8_STAGE(PG8_SB(1, 1), b3 + hstepB, voffB); PG8_STAGE(PG8_SA(1, 0), a3, voffA);
;             PG8_WAIT_V(8); PG8_WAIT_L(0); PG8_BAR; PG8_MMA(1, 0, At, B0); PG8_MMA(1, 1, At, B1); PG8_BAR; PG8_SCHED;
	v_mfma_f32_16x16x32_bf16 v[86:89], v[150:153], v[182:185], v[86:89]
	v_mfma_f32_16x16x32_bf16 v[82:85], v[158:161], v[182:185], v[82:85]
	v_mfma_f32_16x16x32_bf16 v[70:73], v[150:153], v[190:193], v[70:73]
	v_mfma_f32_16x16x32_bf16 v[66:69], v[158:161], v[190:193], v[66:69]
	s_setprio 0
	s_nop 0
	s_add_u32 s30, s8, 0xffff8000
	s_addc_u32 s31, s9, -1
	s_add_i32 s44, s44, s41
	v_lshl_add_u64 v[202:203], s[30:31], 0, v[196:197]
	s_mov_b32 m0, s44
	ds_read_b128 v[162:165], v231 offset:49152
	ds_read_b128 v[166:169], v231 offset:50176
	ds_read_b128 v[170:173], v231 offset:51200
	ds_read_b128 v[174:177], v231 offset:52224
	ds_read_b128 v[178:181], v231 offset:53248
	ds_read_b128 v[182:185], v231 offset:54272
	ds_read_b128 v[186:189], v231 offset:55296
	ds_read_b128 v[190:193], v231 offset:56320
	global_load_lds_dwordx4 v[202:203], off
	s_add_i32 m0, s44, 0x2000
	s_add_u32 s8, s8, 0xffffc000
	v_lshl_add_u64 v[202:203], s[30:31], 0, v[200:201]
	s_addc_u32 s9, s9, -1
	s_add_i32 s30, s65, s41
	global_load_lds_dwordx4 v[202:203], off
	v_lshl_add_u64 v[202:203], s[8:9], 0, v[196:197]
	s_mov_b32 m0, s30
	s_nop 0
	global_load_lds_dwordx4 v[202:203], off
	v_lshl_add_u64 v[202:203], s[8:9], 0, v[200:201]
	s_add_i32 m0, s30, 0x2000
	s_nop 0
	global_load_lds_dwordx4 v[202:203], off
	v_lshl_add_u64 v[202:203], s[34:35], 0, v[194:195]
	s_mov_b32 m0, s71
	s_nop 0
	global_load_lds_dwordx4 v[202:203], off
	v_lshl_add_u64 v[202:203], s[34:35], 0, v[198:199]
	s_mov_b32 m0, s80
	s_nop 0
	global_load_lds_dwordx4 v[202:203], off
	s_waitcnt vmcnt(8)
	s_waitcnt lgkmcnt(0)
	s_barrier
	s_setprio 1
	s_waitcnt lgkmcnt(0)
	v_mfma_f32_16x16x32_bf16 v[62:65], v[130:133], v[162:165], v[62:65]
	v_mfma_f32_16x16x32_bf16 v[58:61], v[138:141], v[162:165], v[58:61]
	v_mfma_f32_16x16x32_bf16 v[46:49], v[130:133], v[170:173], v[46:49]
	v_mfma_f32_16x16x32_bf16 v[42:45], v[138:141], v[170:173], v[42:45]
	v_mfma_f32_16x16x32_bf16 v[30:33], v[130:133], v[178:181], v[30:33]
	v_mfma_f32_16x16x32_bf16 v[26:29], v[138:141], v[178:181], v[26:29]
	v_mfma_f32_16x16x32_bf16 v[14:17], v[130:133], v[186:189], v[14:17]
	v_mfma_f32_16x16x32_bf16 v[10:13], v[138:141], v[186:189], v[10:13]
	v_mfma_f32_16x16x32_bf16 v[62:65], v[134:137], v[166:169], v[62:65]
	v_mfma_f32_16x16x32_bf16 v[58:61], v[142:145], v[166:169], v[58:61]
	v_mfma_f32_16x16x32_bf16 v[46:49], v[134:137], v[174:177], v[46:49]
	v_mfma_f32_16x16x32_bf16 v[42:45], v[142:145], v[174:177], v[42:45]
	v_mfma_f32_16x16x32_bf16 v[30:33], v[134:137], v[182:185], v[30:33]
	v_mfma_f32_16x16x32_bf16 v[26:29], v[142:145], v[182:185], v[26:29]
	v_mfma_f32_16x16x32_bf16 v[14:17], v[134:137], v[190:193], v[14:17]
	v_mfma_f32_16x16x32_bf16 v[10:13], v[142:145], v[190:193], v[10:13]
	s_setprio 0
	s_setprio 1
	v_mfma_f32_16x16x32_bf16 v[54:57], v[146:149], v[162:165], v[54:57]
	v_mfma_f32_16x16x32_bf16 v[50:53], v[154:157], v[162:165], v[50:53]
	v_mfma_f32_16x16x32_bf16 v[38:41], v[146:149], v[170:173], v[38:41]
	v_mfma_f32_16x16x32_bf16 v[34:37], v[154:157], v[170:173], v[34:37]
	v_mfma_f32_16x16x32_bf16 v[22:25], v[146:149], v[178:181], v[22:25]
	v_mfma_f32_16x16x32_bf16 v[18:21], v[154:157], v[178:181], v[18:21]
	v_mfma_f32_16x16x32_bf16 v[6:9], v[146:149], v[186:189], v[6:9]
	v_mfma_f32_16x16x32_bf16 v[2:5], v[154:157], v[186:189], v[2:5]
	v_mfma_f32_16x16x32_bf16 v[54:57], v[150:153], v[166:169], v[54:57]
	v_mfma_f32_16x16x32_bf16 v[50:53], v[158:161], v[166:169], v[50:53]
	v_mfma_f32_16x16x32_bf16 v[38:41], v[150:153], v[174:177], v[38:41]
	v_mfma_f32_16x16x32_bf16 v[34:37], v[158:161], v[174:177], v[34:37]
	s_setprio 2
	s_barrier
	v_mfma_f32_16x16x32_bf16 v[22:25], v[150:153], v[182:185], v[22:25]
	v_mfma_f32_16x16x32_bf16 v[18:21], v[158:161], v[182:185], v[18:21]
	v_mfma_f32_16x16x32_bf16 v[6:9], v[150:153], v[190:193], v[6:9]
	v_mfma_f32_16x16x32_bf16 v[2:5], v[158:161], v[190:193], v[2:5]
	s_setprio 0
	s_nop 0
	s_cmpk_gt_u32 s56, 0x55
	s_mov_b32 s56, s57
	s_cbranch_scc1 .LBB0_1449
